# speedup vs baseline: 1.0155x; 1.0155x over previous
; #define LAS __attribute__((address_space(3)))
; #define MFMA16(a, b, c) __builtin_amdgcn_mfma_f32_16x16x32_bf16((a), (b), (c), 0, 0, 0)
; __device__ __forceinline__ s16x4 tr_read(const LAS unsigned short* p) { return __builtin_amdgcn_ds_read_tr16_b64_v4i16((LAS s16x4*)p); }
; template <int KIND, int MODE>
; __device__ __forceinline__ void scan_unit(Frame& F, int layer, int h, int vhalf, int grp) {
;     ...
;             float decs = 1.f; if (KIND) decs = X[320];
; #pragma unroll
;             for (int i = 0; i < NDT; ++i) {
;                 if (KIND) S[i] = S[i] * decs; else S[i] = S[i] * *(const LAS f32x4*)(X + 1536 + 16 * i + 4 * g);
; #pragma unroll
;                 for (int ks = 0; ks < 2; ++ks) { const LAS unsigned short* kp = K2 + (32 * ks + 8 * g + (li >> 2)) * QST + 16 * i + 4 * (li & 3); const bf16x8 a = cat8(tr_read(kp), tr_read(kp + 4 * QST)); S[i] = MFMA16(a, vf[ks], S[i]); }
;             }
.LBB0_412:
	v_mov_b32_e32 v0, s83
	s_waitcnt lgkmcnt(0)
	s_barrier
	ds_read_b64_tr_b16 v[94:95], v126
	ds_read_b64_tr_b16 v[96:97], v126 offset:1088
	ds_read_b64_tr_b16 v[90:91], v126 offset:8704
	ds_read_b64_tr_b16 v[92:93], v126 offset:9792
	ds_read_b32 v0, v0
	ds_read_b64_tr_b16 v[130:131], v127 offset:2112
	ds_read_b64_tr_b16 v[128:129], v127
	ds_read_b64_tr_b16 v[132:133], v127 offset:32
	s_waitcnt lgkmcnt(0)
	v_pk_mul_f32 v[80:81], v[80:81], v[0:1] op_sel_hi:[1,0]
	v_pk_mul_f32 v[78:79], v[78:79], v[0:1] op_sel_hi:[1,0]
	v_pk_mul_f32 v[76:77], v[76:77], v[0:1] op_sel_hi:[1,0]
	v_pk_mul_f32 v[74:75], v[74:75], v[0:1] op_sel_hi:[1,0]
	v_mfma_f32_16x16x32_bf16 v[78:81], v[128:131], v[94:97], v[78:81]
	ds_read_b64_tr_b16 v[128:129], v127 offset:16896
	ds_read_b64_tr_b16 v[130:131], v127 offset:19008
	ds_read_b64_tr_b16 v[134:135], v127 offset:2144
	v_pk_mul_f32 v[84:85], v[84:85], v[0:1] op_sel_hi:[1,0]
	s_waitcnt lgkmcnt(0)
	v_mfma_f32_16x16x32_bf16 v[78:81], v[128:131], v[90:93], v[78:81]
	ds_read_b64_tr_b16 v[128:129], v127 offset:16928
	ds_read_b64_tr_b16 v[130:131], v127 offset:19040
	v_pk_mul_f32 v[82:83], v[82:83], v[0:1] op_sel_hi:[1,0]
	v_pk_mul_f32 v[72:73], v[72:73], v[0:1] op_sel_hi:[1,0]
	v_mfma_f32_16x16x32_bf16 v[74:77], v[132:135], v[94:97], v[74:77]
	v_mul_f32_e64 v70, v70, v0
	v_mul_f32_e64 v71, v71, v0
	v_pk_mul_f32 v[68:69], v[68:69], v[0:1] op_sel_hi:[1,0]
	v_pk_mul_f32 v[66:67], v[66:67], v[0:1] op_sel_hi:[1,0]
	s_waitcnt lgkmcnt(0)
	v_mfma_f32_16x16x32_bf16 v[74:77], v[128:131], v[90:93], v[74:77]
	ds_read_b64_tr_b16 v[128:129], v127 offset:64
	ds_read_b64_tr_b16 v[130:131], v127 offset:2176
	v_pk_mul_f32 v[64:65], v[64:65], v[0:1] op_sel_hi:[1,0]
	v_pk_mul_f32 v[62:63], v[62:63], v[0:1] op_sel_hi:[1,0]
	s_waitcnt lgkmcnt(0)
	v_mfma_f32_16x16x32_bf16 v[82:85], v[128:131], v[94:97], v[82:85]
	ds_read_b64_tr_b16 v[128:129], v127 offset:16960
	ds_read_b64_tr_b16 v[130:131], v127 offset:19072
	v_pk_mul_f32 v[60:61], v[60:61], v[0:1] op_sel_hi:[1,0]
	v_pk_mul_f32 v[58:59], v[58:59], v[0:1] op_sel_hi:[1,0]
	s_waitcnt lgkmcnt(0)
	v_mfma_f32_16x16x32_bf16 v[82:85], v[128:131], v[90:93], v[82:85]
	ds_read_b64_tr_b16 v[128:129], v127 offset:96
	ds_read_b64_tr_b16 v[130:131], v127 offset:2208
	v_pk_mul_f32 v[56:57], v[56:57], v[0:1] op_sel_hi:[1,0]
	v_pk_mul_f32 v[54:55], v[54:55], v[0:1] op_sel_hi:[1,0]
	s_waitcnt lgkmcnt(0)
	v_mfma_f32_16x16x32_bf16 v[70:73], v[128:131], v[94:97], v[70:73]
	ds_read_b64_tr_b16 v[128:129], v127 offset:16992
	ds_read_b64_tr_b16 v[130:131], v127 offset:19104
	v_pk_mul_f32 v[48:49], v[48:49], v[0:1] op_sel_hi:[1,0]
	v_pk_mul_f32 v[46:47], v[46:47], v[0:1] op_sel_hi:[1,0]
	s_waitcnt lgkmcnt(0)
	v_mfma_f32_16x16x32_bf16 v[70:73], v[128:131], v[90:93], v[70:73]
	ds_read_b64_tr_b16 v[128:129], v127 offset:128
	ds_read_b64_tr_b16 v[130:131], v127 offset:2240
	v_pk_mul_f32 v[44:45], v[44:45], v[0:1] op_sel_hi:[1,0]
	v_pk_mul_f32 v[42:43], v[42:43], v[0:1] op_sel_hi:[1,0]
	s_waitcnt lgkmcnt(0)
	v_mfma_f32_16x16x32_bf16 v[66:69], v[128:131], v[94:97], v[66:69]
	ds_read_b64_tr_b16 v[128:129], v127 offset:17024
	ds_read_b64_tr_b16 v[130:131], v127 offset:19136
	v_pk_mul_f32 v[40:41], v[40:41], v[0:1] op_sel_hi:[1,0]
	v_pk_mul_f32 v[38:39], v[38:39], v[0:1] op_sel_hi:[1,0]
	s_waitcnt lgkmcnt(0)
	v_mfma_f32_16x16x32_bf16 v[66:69], v[128:131], v[90:93], v[66:69]
	ds_read_b64_tr_b16 v[128:129], v127 offset:160
	ds_read_b64_tr_b16 v[130:131], v127 offset:2272
	v_pk_mul_f32 v[32:33], v[32:33], v[0:1] op_sel_hi:[1,0]
	v_pk_mul_f32 v[30:31], v[30:31], v[0:1] op_sel_hi:[1,0]
	s_waitcnt lgkmcnt(0)
	v_mfma_f32_16x16x32_bf16 v[62:65], v[128:131], v[94:97], v[62:65]
	ds_read_b64_tr_b16 v[128:129], v127 offset:17056
	ds_read_b64_tr_b16 v[130:131], v127 offset:19168
	v_pk_mul_f32 v[24:25], v[24:25], v[0:1] op_sel_hi:[1,0]
	v_pk_mul_f32 v[22:23], v[22:23], v[0:1] op_sel_hi:[1,0]
	s_waitcnt lgkmcnt(0)
	v_mfma_f32_16x16x32_bf16 v[62:65], v[128:131], v[90:93], v[62:65]
	ds_read_b64_tr_b16 v[128:129], v127 offset:192
	ds_read_b64_tr_b16 v[130:131], v127 offset:2304
	v_pk_mul_f32 v[4:5], v[4:5], v[0:1] op_sel_hi:[1,0]
	v_pk_mul_f32 v[2:3], v[2:3], v[0:1] op_sel_hi:[1,0]
	s_waitcnt lgkmcnt(0)
	v_mfma_f32_16x16x32_bf16 v[58:61], v[128:131], v[94:97], v[58:61]
	ds_read_b64_tr_b16 v[128:129], v127 offset:17088
	ds_read_b64_tr_b16 v[130:131], v127 offset:19200
	v_pk_mul_f32 v[52:53], v[52:53], v[0:1] op_sel_hi:[1,0]
	v_pk_mul_f32 v[50:51], v[50:51], v[0:1] op_sel_hi:[1,0]
	s_waitcnt lgkmcnt(0)
	v_mfma_f32_16x16x32_bf16 v[58:61], v[128:131], v[90:93], v[58:61]
	ds_read_b64_tr_b16 v[128:129], v127 offset:224
	ds_read_b64_tr_b16 v[130:131], v127 offset:2336
	v_pk_mul_f32 v[88:89], v[88:89], v[0:1] op_sel_hi:[1,0]
	v_pk_mul_f32 v[86:87], v[86:87], v[0:1] op_sel_hi:[1,0]
	s_waitcnt lgkmcnt(0)
	v_mfma_f32_16x16x32_bf16 v[54:57], v[128:131], v[94:97], v[54:57]
	ds_read_b64_tr_b16 v[128:129], v127 offset:17120
	ds_read_b64_tr_b16 v[130:131], v127 offset:19232
	s_waitcnt lgkmcnt(0)
	v_mfma_f32_16x16x32_bf16 v[54:57], v[128:131], v[90:93], v[54:57]
	ds_read_b64_tr_b16 v[128:129], v127 offset:256
	ds_read_b64_tr_b16 v[130:131], v127 offset:2368
	s_waitcnt lgkmcnt(0)
	v_mfma_f32_16x16x32_bf16 v[46:49], v[128:131], v[94:97], v[46:49]
	ds_read_b64_tr_b16 v[128:129], v127 offset:17152
	ds_read_b64_tr_b16 v[130:131], v127 offset:19264
	s_waitcnt lgkmcnt(0)
	v_mfma_f32_16x16x32_bf16 v[46:49], v[128:131], v[90:93], v[46:49]
	ds_read_b64_tr_b16 v[128:129], v127 offset:288
	ds_read_b64_tr_b16 v[130:131], v127 offset:2400
	s_waitcnt lgkmcnt(0)
	v_mfma_f32_16x16x32_bf16 v[42:45], v[128:131], v[94:97], v[42:45]
	ds_read_b64_tr_b16 v[128:129], v127 offset:17184
	ds_read_b64_tr_b16 v[130:131], v127 offset:19296
	s_waitcnt lgkmcnt(0)
; #define LAS __attribute__((address_space(3)))
; #define MFMA16(a, b, c) __builtin_amdgcn_mfma_f32_16x16x32_bf16((a), (b), (c), 0, 0, 0)
; __device__ __forceinline__ s16x4 tr_read(const LAS unsigned short* p) { return __builtin_amdgcn_ds_read_tr16_b64_v4i16((LAS s16x4*)p); }
; template <int KIND, int MODE>
; __device__ __forceinline__ void scan_unit(Frame& F, int layer, int h, int vhalf, int grp) {
;     ...
;                 for (int ks = 0; ks < 2; ++ks) { const LAS unsigned short* kp = K2 + (32 * ks + 8 * g + (li >> 2)) * QST + 16 * i + 4 * (li & 3); const bf16x8 a = cat8(tr_read(kp), tr_read(kp + 4 * QST)); S[i] = MFMA16(a, vf[ks], S[i]); }
;             }
;             if (KIND && tid < 256) { float s = 0.f;
; #pragma unroll 8
;                 for (int t = 0; t < 64; ++t) s += bf2f(K2[t * QST + tid]);
;                 X[384 + tid] = decs * X[384 + tid] + s; }
	v_mfma_f32_16x16x32_bf16 v[42:45], v[128:131], v[90:93], v[42:45]
	ds_read_b64_tr_b16 v[128:129], v127 offset:320
	ds_read_b64_tr_b16 v[130:131], v127 offset:2432
	s_waitcnt lgkmcnt(0)
	v_mfma_f32_16x16x32_bf16 v[38:41], v[128:131], v[94:97], v[38:41]
	ds_read_b64_tr_b16 v[128:129], v127 offset:17216
	ds_read_b64_tr_b16 v[130:131], v127 offset:19328
	s_waitcnt lgkmcnt(0)
	v_mfma_f32_16x16x32_bf16 v[38:41], v[128:131], v[90:93], v[38:41]
	ds_read_b64_tr_b16 v[128:129], v127 offset:352
	ds_read_b64_tr_b16 v[130:131], v127 offset:2464
	s_waitcnt lgkmcnt(0)
	v_mfma_f32_16x16x32_bf16 v[30:33], v[128:131], v[94:97], v[30:33]
	ds_read_b64_tr_b16 v[128:129], v127 offset:17248
	ds_read_b64_tr_b16 v[130:131], v127 offset:19360
	s_waitcnt lgkmcnt(0)
	v_mfma_f32_16x16x32_bf16 v[30:33], v[128:131], v[90:93], v[30:33]
	ds_read_b64_tr_b16 v[128:129], v127 offset:384
	ds_read_b64_tr_b16 v[130:131], v127 offset:2496
	s_waitcnt lgkmcnt(0)
	v_mfma_f32_16x16x32_bf16 v[22:25], v[128:131], v[94:97], v[22:25]
	ds_read_b64_tr_b16 v[128:129], v127 offset:17280
	ds_read_b64_tr_b16 v[130:131], v127 offset:19392
	s_waitcnt lgkmcnt(0)
	v_mfma_f32_16x16x32_bf16 v[22:25], v[128:131], v[90:93], v[22:25]
	ds_read_b64_tr_b16 v[128:129], v127 offset:416
	ds_read_b64_tr_b16 v[130:131], v127 offset:2528
	s_waitcnt lgkmcnt(0)
	v_mfma_f32_16x16x32_bf16 v[2:5], v[128:131], v[94:97], v[2:5]
	ds_read_b64_tr_b16 v[128:129], v127 offset:17312
	ds_read_b64_tr_b16 v[130:131], v127 offset:19424
	s_waitcnt lgkmcnt(0)
	v_mfma_f32_16x16x32_bf16 v[2:5], v[128:131], v[90:93], v[2:5]
	ds_read_b64_tr_b16 v[128:129], v127 offset:448
	ds_read_b64_tr_b16 v[130:131], v127 offset:2560
	s_waitcnt lgkmcnt(0)
	v_mfma_f32_16x16x32_bf16 v[50:53], v[128:131], v[94:97], v[50:53]
	ds_read_b64_tr_b16 v[128:129], v127 offset:17344
	ds_read_b64_tr_b16 v[130:131], v127 offset:19456
	s_waitcnt lgkmcnt(0)
	v_mfma_f32_16x16x32_bf16 v[50:53], v[128:131], v[90:93], v[50:53]
	ds_read_b64_tr_b16 v[128:129], v127 offset:480
	ds_read_b64_tr_b16 v[130:131], v127 offset:2592
	s_waitcnt lgkmcnt(0)
	v_mfma_f32_16x16x32_bf16 v[86:89], v[128:131], v[94:97], v[86:89]
	ds_read_b64_tr_b16 v[94:95], v127 offset:17376
	ds_read_b64_tr_b16 v[96:97], v127 offset:19488
	s_waitcnt lgkmcnt(0)
	v_mfma_f32_16x16x32_bf16 v[86:89], v[94:97], v[90:93], v[86:89]
	s_and_saveexec_b64 s[24:25], s[10:11]
	s_cbranch_execz .LBB0_404
	v_add_u32_e32 v129, 0x10800, v119
	v_mov_b32_e32 v90, 0
	ds_read_u16 v91, v129
	ds_read_u16 v92, v129 offset:528
	ds_read_u16 v93, v129 offset:1056
	ds_read_u16 v94, v129 offset:1584
	ds_read_u16 v95, v129 offset:2112
	ds_read_u16 v96, v129 offset:2640
	ds_read_u16 v97, v129 offset:3168
	ds_read_u16 v128, v129 offset:3696
	s_waitcnt lgkmcnt(7)
	v_lshlrev_b32_e32 v91, 16, v91
	v_add_f32_e32 v90, v90, v91
	ds_read_u16 v91, v129 offset:4224
	s_waitcnt lgkmcnt(7)
	v_lshlrev_b32_e32 v92, 16, v92
	v_add_f32_e32 v90, v90, v92
	ds_read_u16 v92, v129 offset:4752
	s_waitcnt lgkmcnt(7)
	v_lshlrev_b32_e32 v93, 16, v93
	v_add_f32_e32 v90, v90, v93
	ds_read_u16 v93, v129 offset:5280
	s_waitcnt lgkmcnt(7)
	v_lshlrev_b32_e32 v94, 16, v94
	v_add_f32_e32 v90, v90, v94
	ds_read_u16 v94, v129 offset:5808
	s_waitcnt lgkmcnt(7)
	v_lshlrev_b32_e32 v95, 16, v95
	v_add_f32_e32 v90, v90, v95
	ds_read_u16 v95, v129 offset:6336
	s_waitcnt lgkmcnt(7)
	v_lshlrev_b32_e32 v96, 16, v96
	v_add_f32_e32 v90, v90, v96
	ds_read_u16 v96, v129 offset:6864
	s_waitcnt lgkmcnt(7)
	v_lshlrev_b32_e32 v97, 16, v97
	v_add_f32_e32 v90, v90, v97
	ds_read_u16 v97, v129 offset:7392
	s_waitcnt lgkmcnt(7)
	v_lshlrev_b32_e32 v128, 16, v128
	v_add_f32_e32 v90, v90, v128
	ds_read_u16 v128, v129 offset:7920
	s_waitcnt lgkmcnt(7)
	v_lshlrev_b32_e32 v91, 16, v91
	v_add_f32_e32 v90, v90, v91
	ds_read_u16 v91, v129 offset:8448
	s_waitcnt lgkmcnt(7)
	v_lshlrev_b32_e32 v92, 16, v92
	v_add_f32_e32 v90, v90, v92
	ds_read_u16 v92, v129 offset:8976
	s_waitcnt lgkmcnt(7)
	v_lshlrev_b32_e32 v93, 16, v93
	v_add_f32_e32 v90, v90, v93
	ds_read_u16 v93, v129 offset:9504
	s_waitcnt lgkmcnt(7)
	v_lshlrev_b32_e32 v94, 16, v94
	v_add_f32_e32 v90, v90, v94
	ds_read_u16 v94, v129 offset:10032
	s_waitcnt lgkmcnt(7)
	v_lshlrev_b32_e32 v95, 16, v95
	v_add_f32_e32 v90, v90, v95
	ds_read_u16 v95, v129 offset:10560
	s_waitcnt lgkmcnt(7)
	v_lshlrev_b32_e32 v96, 16, v96
	v_add_f32_e32 v90, v90, v96
	ds_read_u16 v96, v129 offset:11088
	s_waitcnt lgkmcnt(7)
	v_lshlrev_b32_e32 v97, 16, v97
	v_add_f32_e32 v90, v90, v97
	ds_read_u16 v97, v129 offset:11616
	s_waitcnt lgkmcnt(7)
	v_lshlrev_b32_e32 v128, 16, v128
	v_add_f32_e32 v90, v90, v128
	ds_read_u16 v128, v129 offset:12144
	s_waitcnt lgkmcnt(7)
	v_lshlrev_b32_e32 v91, 16, v91
	v_add_f32_e32 v90, v90, v91
	ds_read_u16 v91, v129 offset:12672
	s_waitcnt lgkmcnt(7)
	v_lshlrev_b32_e32 v92, 16, v92
	v_add_f32_e32 v90, v90, v92
	ds_read_u16 v92, v129 offset:13200
	s_waitcnt lgkmcnt(7)
	v_lshlrev_b32_e32 v93, 16, v93
	v_add_f32_e32 v90, v90, v93
	ds_read_u16 v93, v129 offset:13728
	s_waitcnt lgkmcnt(7)
	v_lshlrev_b32_e32 v94, 16, v94
	v_add_f32_e32 v90, v90, v94
	ds_read_u16 v94, v129 offset:14256
	s_waitcnt lgkmcnt(7)
; template <int KIND, int MODE>
; __device__ __forceinline__ void scan_unit(Frame& F, int layer, int h, int vhalf, int grp) {
;     ...
;             if (KIND && tid < 256) { float s = 0.f;
; #pragma unroll 8
;                 for (int t = 0; t < 64; ++t) s += bf2f(K2[t * QST + tid]);
;                 X[384 + tid] = decs * X[384 + tid] + s; }
	v_lshlrev_b32_e32 v95, 16, v95
	v_add_f32_e32 v90, v90, v95
	ds_read_u16 v95, v129 offset:14784
	s_waitcnt lgkmcnt(7)
	v_lshlrev_b32_e32 v96, 16, v96
	v_add_f32_e32 v90, v90, v96
	ds_read_u16 v96, v129 offset:15312
	s_waitcnt lgkmcnt(7)
	v_lshlrev_b32_e32 v97, 16, v97
	v_add_f32_e32 v90, v90, v97
	ds_read_u16 v97, v129 offset:15840
	s_waitcnt lgkmcnt(7)
	v_lshlrev_b32_e32 v128, 16, v128
	v_add_f32_e32 v90, v90, v128
	ds_read_u16 v128, v129 offset:16368
	s_waitcnt lgkmcnt(7)
	v_lshlrev_b32_e32 v91, 16, v91
	v_add_f32_e32 v90, v90, v91
	ds_read_u16 v91, v129 offset:16896
	s_waitcnt lgkmcnt(7)
	v_lshlrev_b32_e32 v92, 16, v92
	v_add_f32_e32 v90, v90, v92
	ds_read_u16 v92, v129 offset:17424
	s_waitcnt lgkmcnt(7)
	v_lshlrev_b32_e32 v93, 16, v93
	v_add_f32_e32 v90, v90, v93
	ds_read_u16 v93, v129 offset:17952
	s_waitcnt lgkmcnt(7)
	v_lshlrev_b32_e32 v94, 16, v94
	v_add_f32_e32 v90, v90, v94
	ds_read_u16 v94, v129 offset:18480
	s_waitcnt lgkmcnt(7)
	v_lshlrev_b32_e32 v95, 16, v95
	v_add_f32_e32 v90, v90, v95
	ds_read_u16 v95, v129 offset:19008
	s_waitcnt lgkmcnt(7)
	v_lshlrev_b32_e32 v96, 16, v96
	v_add_f32_e32 v90, v90, v96
	ds_read_u16 v96, v129 offset:19536
	s_waitcnt lgkmcnt(7)
	v_lshlrev_b32_e32 v97, 16, v97
	v_add_f32_e32 v90, v90, v97
	ds_read_u16 v97, v129 offset:20064
	s_waitcnt lgkmcnt(7)
	v_lshlrev_b32_e32 v128, 16, v128
	v_add_f32_e32 v90, v90, v128
	ds_read_u16 v128, v129 offset:20592
	s_waitcnt lgkmcnt(7)
	v_lshlrev_b32_e32 v91, 16, v91
	v_add_f32_e32 v90, v90, v91
	ds_read_u16 v91, v129 offset:21120
	s_waitcnt lgkmcnt(7)
	v_lshlrev_b32_e32 v92, 16, v92
	v_add_f32_e32 v90, v90, v92
	ds_read_u16 v92, v129 offset:21648
	s_waitcnt lgkmcnt(7)
	v_lshlrev_b32_e32 v93, 16, v93
	v_add_f32_e32 v90, v90, v93
	ds_read_u16 v93, v129 offset:22176
	s_waitcnt lgkmcnt(7)
	v_lshlrev_b32_e32 v94, 16, v94
	v_add_f32_e32 v90, v90, v94
	ds_read_u16 v94, v129 offset:22704
	s_waitcnt lgkmcnt(7)
	v_lshlrev_b32_e32 v95, 16, v95
	v_add_f32_e32 v90, v90, v95
	ds_read_u16 v95, v129 offset:23232
	s_waitcnt lgkmcnt(7)
	v_lshlrev_b32_e32 v96, 16, v96
	v_add_f32_e32 v90, v90, v96
	ds_read_u16 v96, v129 offset:23760
	s_waitcnt lgkmcnt(7)
	v_lshlrev_b32_e32 v97, 16, v97
	v_add_f32_e32 v90, v90, v97
	ds_read_u16 v97, v129 offset:24288
	s_waitcnt lgkmcnt(7)
	v_lshlrev_b32_e32 v128, 16, v128
	v_add_f32_e32 v90, v90, v128
	ds_read_u16 v128, v129 offset:24816
	s_waitcnt lgkmcnt(7)
	v_lshlrev_b32_e32 v91, 16, v91
	v_add_f32_e32 v90, v90, v91
	ds_read_u16 v91, v129 offset:25344
	s_waitcnt lgkmcnt(7)
	v_lshlrev_b32_e32 v92, 16, v92
	v_add_f32_e32 v90, v90, v92
	ds_read_u16 v92, v129 offset:25872
	s_waitcnt lgkmcnt(7)
	v_lshlrev_b32_e32 v93, 16, v93
	v_add_f32_e32 v90, v90, v93
	ds_read_u16 v93, v129 offset:26400
	s_waitcnt lgkmcnt(7)
	v_lshlrev_b32_e32 v94, 16, v94
	v_add_f32_e32 v90, v90, v94
	ds_read_u16 v94, v129 offset:26928
	s_waitcnt lgkmcnt(7)
	v_lshlrev_b32_e32 v95, 16, v95
	v_add_f32_e32 v90, v90, v95
	ds_read_u16 v95, v129 offset:27456
	s_waitcnt lgkmcnt(7)
	v_lshlrev_b32_e32 v96, 16, v96
	v_add_f32_e32 v90, v90, v96
	ds_read_u16 v96, v129 offset:27984
	s_waitcnt lgkmcnt(7)
	v_lshlrev_b32_e32 v97, 16, v97
	v_add_f32_e32 v90, v90, v97
	ds_read_u16 v97, v129 offset:28512
	s_waitcnt lgkmcnt(7)
	v_lshlrev_b32_e32 v128, 16, v128
	v_add_f32_e32 v90, v90, v128
	ds_read_u16 v128, v129 offset:29040
	s_waitcnt lgkmcnt(7)
	v_lshlrev_b32_e32 v91, 16, v91
	v_add_f32_e32 v90, v90, v91
	ds_read_u16 v91, v129 offset:29568
	s_waitcnt lgkmcnt(7)
	v_lshlrev_b32_e32 v92, 16, v92
	v_add_f32_e32 v90, v90, v92
	ds_read_u16 v92, v129 offset:30096
	s_waitcnt lgkmcnt(7)
	v_lshlrev_b32_e32 v93, 16, v93
	v_add_f32_e32 v90, v90, v93
	ds_read_u16 v93, v129 offset:30624
	s_waitcnt lgkmcnt(7)
	v_lshlrev_b32_e32 v94, 16, v94
	v_add_f32_e32 v90, v90, v94
	ds_read_u16 v94, v129 offset:31152
	s_waitcnt lgkmcnt(7)
	v_lshlrev_b32_e32 v95, 16, v95
	v_add_f32_e32 v90, v90, v95
	ds_read_u16 v95, v129 offset:31680
	s_waitcnt lgkmcnt(7)
	v_lshlrev_b32_e32 v96, 16, v96
	v_add_f32_e32 v90, v90, v96
	ds_read_u16 v96, v129 offset:32208
	s_waitcnt lgkmcnt(7)
	v_lshlrev_b32_e32 v97, 16, v97
	v_add_f32_e32 v90, v90, v97
	ds_read_u16 v97, v129 offset:32736
	s_waitcnt lgkmcnt(7)
	v_lshlrev_b32_e32 v128, 16, v128
	v_add_f32_e32 v90, v90, v128
	ds_read_u16 v128, v129 offset:33264
	s_waitcnt lgkmcnt(7)
	v_lshlrev_b32_e32 v91, 16, v91
	v_add_f32_e32 v90, v90, v91
	s_waitcnt lgkmcnt(6)
	v_lshlrev_b32_e32 v92, 16, v92
	v_add_f32_e32 v90, v90, v92
	s_waitcnt lgkmcnt(5)
	v_lshlrev_b32_e32 v93, 16, v93
	v_add_f32_e32 v90, v90, v93
	s_waitcnt lgkmcnt(4)
	v_lshlrev_b32_e32 v94, 16, v94
	v_add_f32_e32 v90, v90, v94
	s_waitcnt lgkmcnt(3)
	v_lshlrev_b32_e32 v95, 16, v95
	v_add_f32_e32 v90, v90, v95
	s_waitcnt lgkmcnt(2)
	v_lshlrev_b32_e32 v96, 16, v96
	v_add_f32_e32 v90, v90, v96
	s_waitcnt lgkmcnt(1)
	v_lshlrev_b32_e32 v97, 16, v97
	v_add_f32_e32 v90, v90, v97
	s_waitcnt lgkmcnt(0)
	v_lshlrev_b32_e32 v128, 16, v128
	v_add_f32_e32 v90, v90, v128
	ds_read_b32 v91, v104 offset:1536
	s_waitcnt lgkmcnt(0)
	v_fmac_f32_e32 v90, v0, v91
	ds_write_b32 v104, v90 offset:1536
	s_branch .LBB0_404

; #define LAS __attribute__((address_space(3)))
; #define MFMA16(a, b, c) __builtin_amdgcn_mfma_f32_16x16x32_bf16((a), (b), (c), 0, 0, 0)
; __device__ __forceinline__ s16x4 tr_read(const LAS unsigned short* p) { return __builtin_amdgcn_ds_read_tr16_b64_v4i16((LAS s16x4*)p); }
; template <int KIND, int MODE>
; __device__ __forceinline__ void scan_unit(Frame& F, int layer, int h, int vhalf, int grp) {
;     ...
;             float decs = 1.f; if (KIND) decs = X[320];
; #pragma unroll
;             for (int i = 0; i < NDT; ++i) {
;                 if (KIND) S[i] = S[i] * decs; else S[i] = S[i] * *(const LAS f32x4*)(X + 1536 + 16 * i + 4 * g);
; #pragma unroll
;                 for (int ks = 0; ks < 2; ++ks) { const LAS unsigned short* kp = K2 + (32 * ks + 8 * g + (li >> 2)) * QST + 16 * i + 4 * (li & 3); const bf16x8 a = cat8(tr_read(kp), tr_read(kp + 4 * QST)); S[i] = MFMA16(a, vf[ks], S[i]); }
;             }
.LBB0_544:
	s_or_b64 exec, exec, s[0:1]
	v_mov_b32_e32 v0, s83
	ds_read_b32 v0, v0
	ds_read_b64_tr_b16 v[78:79], v204 offset:2112
	s_waitcnt lgkmcnt(0)
	ds_read_b64_tr_b16 v[76:77], v204
	ds_read_b64_tr_b16 v[80:81], v204 offset:32
	v_pk_mul_f32 v[26:27], v[0:1], v[26:27] op_sel_hi:[0,1]
	v_pk_mul_f32 v[24:25], v[0:1], v[24:25] op_sel_hi:[0,1]
	v_pk_mul_f32 v[6:7], v[0:1], v[6:7] op_sel_hi:[0,1]
	v_pk_mul_f32 v[4:5], v[0:1], v[4:5] op_sel_hi:[0,1]
	s_waitcnt lgkmcnt(0)
	v_mfma_f32_16x16x32_bf16 v[24:27], v[76:79], v[72:75], v[24:27]
	ds_read_b64_tr_b16 v[76:77], v204 offset:16896
	ds_read_b64_tr_b16 v[78:79], v204 offset:19008
	ds_read_b64_tr_b16 v[82:83], v204 offset:2144
	v_pk_mul_f32 v[62:63], v[0:1], v[62:63] op_sel_hi:[0,1]
	s_waitcnt lgkmcnt(0)
	v_mfma_f32_16x16x32_bf16 v[24:27], v[76:79], v[68:71], v[24:27]
	ds_read_b64_tr_b16 v[76:77], v204 offset:16928
	ds_read_b64_tr_b16 v[78:79], v204 offset:19040
	v_pk_mul_f32 v[60:61], v[0:1], v[60:61] op_sel_hi:[0,1]
	v_pk_mul_f32 v[10:11], v[0:1], v[10:11] op_sel_hi:[0,1]
	v_mfma_f32_16x16x32_bf16 v[4:7], v[80:83], v[72:75], v[4:7]
	v_mul_f32_e64 v8, v0, v8
	v_mul_f32_e64 v9, v0, v9
	v_pk_mul_f32 v[14:15], v[0:1], v[14:15] op_sel_hi:[0,1]
	v_pk_mul_f32 v[12:13], v[0:1], v[12:13] op_sel_hi:[0,1]
	s_waitcnt lgkmcnt(0)
	v_mfma_f32_16x16x32_bf16 v[4:7], v[76:79], v[68:71], v[4:7]
	ds_read_b64_tr_b16 v[76:77], v204 offset:64
	ds_read_b64_tr_b16 v[78:79], v204 offset:2176
	v_pk_mul_f32 v[18:19], v[0:1], v[18:19] op_sel_hi:[0,1]
	v_pk_mul_f32 v[16:17], v[0:1], v[16:17] op_sel_hi:[0,1]
	s_waitcnt lgkmcnt(0)
	v_mfma_f32_16x16x32_bf16 v[60:63], v[76:79], v[72:75], v[60:63]
	ds_read_b64_tr_b16 v[76:77], v204 offset:16960
	ds_read_b64_tr_b16 v[78:79], v204 offset:19072
	v_pk_mul_f32 v[22:23], v[0:1], v[22:23] op_sel_hi:[0,1]
	v_pk_mul_f32 v[20:21], v[0:1], v[20:21] op_sel_hi:[0,1]
	s_waitcnt lgkmcnt(0)
	v_mfma_f32_16x16x32_bf16 v[60:63], v[76:79], v[68:71], v[60:63]
	ds_read_b64_tr_b16 v[76:77], v204 offset:96
	ds_read_b64_tr_b16 v[78:79], v204 offset:2208
	v_pk_mul_f32 v[30:31], v[0:1], v[30:31] op_sel_hi:[0,1]
	v_pk_mul_f32 v[28:29], v[0:1], v[28:29] op_sel_hi:[0,1]
	s_waitcnt lgkmcnt(0)
	v_mfma_f32_16x16x32_bf16 v[8:11], v[76:79], v[72:75], v[8:11]
	ds_read_b64_tr_b16 v[76:77], v204 offset:16992
	ds_read_b64_tr_b16 v[78:79], v204 offset:19104
	v_pk_mul_f32 v[34:35], v[0:1], v[34:35] op_sel_hi:[0,1]
	v_pk_mul_f32 v[32:33], v[0:1], v[32:33] op_sel_hi:[0,1]
	s_waitcnt lgkmcnt(0)
	v_mfma_f32_16x16x32_bf16 v[8:11], v[76:79], v[68:71], v[8:11]
	ds_read_b64_tr_b16 v[76:77], v204 offset:128
	ds_read_b64_tr_b16 v[78:79], v204 offset:2240
	v_pk_mul_f32 v[38:39], v[0:1], v[38:39] op_sel_hi:[0,1]
	v_pk_mul_f32 v[36:37], v[0:1], v[36:37] op_sel_hi:[0,1]
	s_waitcnt lgkmcnt(0)
	v_mfma_f32_16x16x32_bf16 v[12:15], v[76:79], v[72:75], v[12:15]
	ds_read_b64_tr_b16 v[76:77], v204 offset:17024
	ds_read_b64_tr_b16 v[78:79], v204 offset:19136
	v_pk_mul_f32 v[42:43], v[0:1], v[42:43] op_sel_hi:[0,1]
	v_pk_mul_f32 v[40:41], v[0:1], v[40:41] op_sel_hi:[0,1]
	s_waitcnt lgkmcnt(0)
	v_mfma_f32_16x16x32_bf16 v[12:15], v[76:79], v[68:71], v[12:15]
	ds_read_b64_tr_b16 v[76:77], v204 offset:160
	ds_read_b64_tr_b16 v[78:79], v204 offset:2272
	v_pk_mul_f32 v[46:47], v[0:1], v[46:47] op_sel_hi:[0,1]
	v_pk_mul_f32 v[44:45], v[0:1], v[44:45] op_sel_hi:[0,1]
	s_waitcnt lgkmcnt(0)
	v_mfma_f32_16x16x32_bf16 v[16:19], v[76:79], v[72:75], v[16:19]
	ds_read_b64_tr_b16 v[76:77], v204 offset:17056
	ds_read_b64_tr_b16 v[78:79], v204 offset:19168
	v_pk_mul_f32 v[50:51], v[0:1], v[50:51] op_sel_hi:[0,1]
	v_pk_mul_f32 v[48:49], v[0:1], v[48:49] op_sel_hi:[0,1]
	s_waitcnt lgkmcnt(0)
	v_mfma_f32_16x16x32_bf16 v[16:19], v[76:79], v[68:71], v[16:19]
	ds_read_b64_tr_b16 v[76:77], v204 offset:192
	ds_read_b64_tr_b16 v[78:79], v204 offset:2304
	v_pk_mul_f32 v[54:55], v[0:1], v[54:55] op_sel_hi:[0,1]
	v_pk_mul_f32 v[52:53], v[0:1], v[52:53] op_sel_hi:[0,1]
	s_waitcnt lgkmcnt(0)
	v_mfma_f32_16x16x32_bf16 v[20:23], v[76:79], v[72:75], v[20:23]
	ds_read_b64_tr_b16 v[76:77], v204 offset:17088
	ds_read_b64_tr_b16 v[78:79], v204 offset:19200
	v_pk_mul_f32 v[58:59], v[0:1], v[58:59] op_sel_hi:[0,1]
	v_pk_mul_f32 v[56:57], v[0:1], v[56:57] op_sel_hi:[0,1]
	s_waitcnt lgkmcnt(0)
	v_mfma_f32_16x16x32_bf16 v[20:23], v[76:79], v[68:71], v[20:23]
	ds_read_b64_tr_b16 v[76:77], v204 offset:224
	ds_read_b64_tr_b16 v[78:79], v204 offset:2336
	v_pk_mul_f32 v[66:67], v[0:1], v[66:67] op_sel_hi:[0,1]
	v_pk_mul_f32 v[64:65], v[0:1], v[64:65] op_sel_hi:[0,1]
	s_waitcnt lgkmcnt(0)
	v_mfma_f32_16x16x32_bf16 v[28:31], v[76:79], v[72:75], v[28:31]
	ds_read_b64_tr_b16 v[76:77], v204 offset:17120
	ds_read_b64_tr_b16 v[78:79], v204 offset:19232
	s_waitcnt lgkmcnt(0)
	v_mfma_f32_16x16x32_bf16 v[28:31], v[76:79], v[68:71], v[28:31]
	ds_read_b64_tr_b16 v[76:77], v204 offset:256
	ds_read_b64_tr_b16 v[78:79], v204 offset:2368
	s_waitcnt lgkmcnt(0)
	v_mfma_f32_16x16x32_bf16 v[32:35], v[76:79], v[72:75], v[32:35]
	ds_read_b64_tr_b16 v[76:77], v204 offset:17152
	ds_read_b64_tr_b16 v[78:79], v204 offset:19264
	s_waitcnt lgkmcnt(0)
	v_mfma_f32_16x16x32_bf16 v[32:35], v[76:79], v[68:71], v[32:35]
	ds_read_b64_tr_b16 v[76:77], v204 offset:288
	ds_read_b64_tr_b16 v[78:79], v204 offset:2400
	s_waitcnt lgkmcnt(0)
	v_mfma_f32_16x16x32_bf16 v[36:39], v[76:79], v[72:75], v[36:39]
	ds_read_b64_tr_b16 v[76:77], v204 offset:17184
	ds_read_b64_tr_b16 v[78:79], v204 offset:19296
	s_waitcnt lgkmcnt(0)
	v_mfma_f32_16x16x32_bf16 v[36:39], v[76:79], v[68:71], v[36:39]
	ds_read_b64_tr_b16 v[76:77], v204 offset:320
	ds_read_b64_tr_b16 v[78:79], v204 offset:2432
	s_waitcnt lgkmcnt(0)
; #define LAS __attribute__((address_space(3)))
; #define MFMA16(a, b, c) __builtin_amdgcn_mfma_f32_16x16x32_bf16((a), (b), (c), 0, 0, 0)
; __device__ __forceinline__ s16x4 tr_read(const LAS unsigned short* p) { return __builtin_amdgcn_ds_read_tr16_b64_v4i16((LAS s16x4*)p); }
; template <int KIND, int MODE>
; __device__ __forceinline__ void scan_unit(Frame& F, int layer, int h, int vhalf, int grp) {
;     ...
;                 for (int ks = 0; ks < 2; ++ks) { const LAS unsigned short* kp = K2 + (32 * ks + 8 * g + (li >> 2)) * QST + 16 * i + 4 * (li & 3); const bf16x8 a = cat8(tr_read(kp), tr_read(kp + 4 * QST)); S[i] = MFMA16(a, vf[ks], S[i]); }
;             }
;             if (KIND && tid < 256) { float s = 0.f;
; #pragma unroll 8
;                 for (int t = 0; t < 64; ++t) s += bf2f(K2[t * QST + tid]);
;                 X[384 + tid] = decs * X[384 + tid] + s; }
	v_mfma_f32_16x16x32_bf16 v[40:43], v[76:79], v[72:75], v[40:43]
	ds_read_b64_tr_b16 v[76:77], v204 offset:17216
	ds_read_b64_tr_b16 v[78:79], v204 offset:19328
	s_waitcnt lgkmcnt(0)
	v_mfma_f32_16x16x32_bf16 v[40:43], v[76:79], v[68:71], v[40:43]
	ds_read_b64_tr_b16 v[76:77], v204 offset:352
	ds_read_b64_tr_b16 v[78:79], v204 offset:2464
	s_waitcnt lgkmcnt(0)
	v_mfma_f32_16x16x32_bf16 v[44:47], v[76:79], v[72:75], v[44:47]
	ds_read_b64_tr_b16 v[76:77], v204 offset:17248
	ds_read_b64_tr_b16 v[78:79], v204 offset:19360
	s_waitcnt lgkmcnt(0)
	v_mfma_f32_16x16x32_bf16 v[44:47], v[76:79], v[68:71], v[44:47]
	ds_read_b64_tr_b16 v[76:77], v204 offset:384
	ds_read_b64_tr_b16 v[78:79], v204 offset:2496
	s_waitcnt lgkmcnt(0)
	v_mfma_f32_16x16x32_bf16 v[48:51], v[76:79], v[72:75], v[48:51]
	ds_read_b64_tr_b16 v[76:77], v204 offset:17280
	ds_read_b64_tr_b16 v[78:79], v204 offset:19392
	s_waitcnt lgkmcnt(0)
	v_mfma_f32_16x16x32_bf16 v[48:51], v[76:79], v[68:71], v[48:51]
	ds_read_b64_tr_b16 v[76:77], v204 offset:416
	ds_read_b64_tr_b16 v[78:79], v204 offset:2528
	s_waitcnt lgkmcnt(0)
	v_mfma_f32_16x16x32_bf16 v[52:55], v[76:79], v[72:75], v[52:55]
	ds_read_b64_tr_b16 v[76:77], v204 offset:17312
	ds_read_b64_tr_b16 v[78:79], v204 offset:19424
	s_waitcnt lgkmcnt(0)
	v_mfma_f32_16x16x32_bf16 v[52:55], v[76:79], v[68:71], v[52:55]
	ds_read_b64_tr_b16 v[76:77], v204 offset:448
	ds_read_b64_tr_b16 v[78:79], v204 offset:2560
	s_waitcnt lgkmcnt(0)
	v_mfma_f32_16x16x32_bf16 v[56:59], v[76:79], v[72:75], v[56:59]
	ds_read_b64_tr_b16 v[76:77], v204 offset:17344
	ds_read_b64_tr_b16 v[78:79], v204 offset:19456
	s_waitcnt lgkmcnt(0)
	v_mfma_f32_16x16x32_bf16 v[56:59], v[76:79], v[68:71], v[56:59]
	ds_read_b64_tr_b16 v[76:77], v204 offset:480
	ds_read_b64_tr_b16 v[78:79], v204 offset:2592
	s_waitcnt lgkmcnt(0)
	v_mfma_f32_16x16x32_bf16 v[64:67], v[76:79], v[72:75], v[64:67]
	ds_read_b64_tr_b16 v[72:73], v204 offset:17376
	ds_read_b64_tr_b16 v[74:75], v204 offset:19488
	s_waitcnt lgkmcnt(0)
	v_mfma_f32_16x16x32_bf16 v[64:67], v[72:75], v[68:71], v[64:67]
	s_and_saveexec_b64 s[42:43], s[8:9]
	s_cbranch_execz .LBB0_548
	v_add_u32_e32 v69, 0x10800, v195
	v_mov_b32_e32 v68, 0
	ds_read_u16 v70, v69
	ds_read_u16 v71, v69 offset:528
	ds_read_u16 v72, v69 offset:1056
	ds_read_u16 v73, v69 offset:1584
	ds_read_u16 v74, v69 offset:2112
	ds_read_u16 v75, v69 offset:2640
	ds_read_u16 v76, v69 offset:3168
	ds_read_u16 v77, v69 offset:3696
	s_waitcnt lgkmcnt(7)
	v_lshlrev_b32_e32 v70, 16, v70
	v_add_f32_e32 v68, v68, v70
	ds_read_u16 v70, v69 offset:4224
	s_waitcnt lgkmcnt(7)
	v_lshlrev_b32_e32 v71, 16, v71
	v_add_f32_e32 v68, v68, v71
	ds_read_u16 v71, v69 offset:4752
	s_waitcnt lgkmcnt(7)
	v_lshlrev_b32_e32 v72, 16, v72
	v_add_f32_e32 v68, v68, v72
	ds_read_u16 v72, v69 offset:5280
	s_waitcnt lgkmcnt(7)
	v_lshlrev_b32_e32 v73, 16, v73
	v_add_f32_e32 v68, v68, v73
	ds_read_u16 v73, v69 offset:5808
	s_waitcnt lgkmcnt(7)
	v_lshlrev_b32_e32 v74, 16, v74
	v_add_f32_e32 v68, v68, v74
	ds_read_u16 v74, v69 offset:6336
	s_waitcnt lgkmcnt(7)
	v_lshlrev_b32_e32 v75, 16, v75
	v_add_f32_e32 v68, v68, v75
	ds_read_u16 v75, v69 offset:6864
	s_waitcnt lgkmcnt(7)
	v_lshlrev_b32_e32 v76, 16, v76
	v_add_f32_e32 v68, v68, v76
	ds_read_u16 v76, v69 offset:7392
	s_waitcnt lgkmcnt(7)
	v_lshlrev_b32_e32 v77, 16, v77
	v_add_f32_e32 v68, v68, v77
	ds_read_u16 v77, v69 offset:7920
	s_waitcnt lgkmcnt(7)
	v_lshlrev_b32_e32 v70, 16, v70
	v_add_f32_e32 v68, v68, v70
	ds_read_u16 v70, v69 offset:8448
	s_waitcnt lgkmcnt(7)
	v_lshlrev_b32_e32 v71, 16, v71
	v_add_f32_e32 v68, v68, v71
	ds_read_u16 v71, v69 offset:8976
	s_waitcnt lgkmcnt(7)
	v_lshlrev_b32_e32 v72, 16, v72
	v_add_f32_e32 v68, v68, v72
	ds_read_u16 v72, v69 offset:9504
	s_waitcnt lgkmcnt(7)
	v_lshlrev_b32_e32 v73, 16, v73
	v_add_f32_e32 v68, v68, v73
	ds_read_u16 v73, v69 offset:10032
	s_waitcnt lgkmcnt(7)
	v_lshlrev_b32_e32 v74, 16, v74
	v_add_f32_e32 v68, v68, v74
	ds_read_u16 v74, v69 offset:10560
	s_waitcnt lgkmcnt(7)
	v_lshlrev_b32_e32 v75, 16, v75
	v_add_f32_e32 v68, v68, v75
	ds_read_u16 v75, v69 offset:11088
	s_waitcnt lgkmcnt(7)
	v_lshlrev_b32_e32 v76, 16, v76
	v_add_f32_e32 v68, v68, v76
	ds_read_u16 v76, v69 offset:11616
	s_waitcnt lgkmcnt(7)
	v_lshlrev_b32_e32 v77, 16, v77
	v_add_f32_e32 v68, v68, v77
	ds_read_u16 v77, v69 offset:12144
	s_waitcnt lgkmcnt(7)
	v_lshlrev_b32_e32 v70, 16, v70
	v_add_f32_e32 v68, v68, v70
	ds_read_u16 v70, v69 offset:12672
	s_waitcnt lgkmcnt(7)
	v_lshlrev_b32_e32 v71, 16, v71
	v_add_f32_e32 v68, v68, v71
	ds_read_u16 v71, v69 offset:13200
	s_waitcnt lgkmcnt(7)
	v_lshlrev_b32_e32 v72, 16, v72
	v_add_f32_e32 v68, v68, v72
	ds_read_u16 v72, v69 offset:13728
	s_waitcnt lgkmcnt(7)
	v_lshlrev_b32_e32 v73, 16, v73
	v_add_f32_e32 v68, v68, v73
	ds_read_u16 v73, v69 offset:14256
	s_waitcnt lgkmcnt(7)
	v_lshlrev_b32_e32 v74, 16, v74
	v_add_f32_e32 v68, v68, v74
	ds_read_u16 v74, v69 offset:14784
	s_waitcnt lgkmcnt(7)
; template <int KIND, int MODE>
; __device__ __forceinline__ void scan_unit(Frame& F, int layer, int h, int vhalf, int grp) {
;     ...
;             if (KIND && tid < 256) { float s = 0.f;
; #pragma unroll 8
;                 for (int t = 0; t < 64; ++t) s += bf2f(K2[t * QST + tid]);
;                 X[384 + tid] = decs * X[384 + tid] + s; }
	v_lshlrev_b32_e32 v75, 16, v75
	v_add_f32_e32 v68, v68, v75
	ds_read_u16 v75, v69 offset:15312
	s_waitcnt lgkmcnt(7)
	v_lshlrev_b32_e32 v76, 16, v76
	v_add_f32_e32 v68, v68, v76
	ds_read_u16 v76, v69 offset:15840
	s_waitcnt lgkmcnt(7)
	v_lshlrev_b32_e32 v77, 16, v77
	v_add_f32_e32 v68, v68, v77
	ds_read_u16 v77, v69 offset:16368
	s_waitcnt lgkmcnt(7)
	v_lshlrev_b32_e32 v70, 16, v70
	v_add_f32_e32 v68, v68, v70
	ds_read_u16 v70, v69 offset:16896
	s_waitcnt lgkmcnt(7)
	v_lshlrev_b32_e32 v71, 16, v71
	v_add_f32_e32 v68, v68, v71
	ds_read_u16 v71, v69 offset:17424
	s_waitcnt lgkmcnt(7)
	v_lshlrev_b32_e32 v72, 16, v72
	v_add_f32_e32 v68, v68, v72
	ds_read_u16 v72, v69 offset:17952
	s_waitcnt lgkmcnt(7)
	v_lshlrev_b32_e32 v73, 16, v73
	v_add_f32_e32 v68, v68, v73
	ds_read_u16 v73, v69 offset:18480
	s_waitcnt lgkmcnt(7)
	v_lshlrev_b32_e32 v74, 16, v74
	v_add_f32_e32 v68, v68, v74
	ds_read_u16 v74, v69 offset:19008
	s_waitcnt lgkmcnt(7)
	v_lshlrev_b32_e32 v75, 16, v75
	v_add_f32_e32 v68, v68, v75
	ds_read_u16 v75, v69 offset:19536
	s_waitcnt lgkmcnt(7)
	v_lshlrev_b32_e32 v76, 16, v76
	v_add_f32_e32 v68, v68, v76
	ds_read_u16 v76, v69 offset:20064
	s_waitcnt lgkmcnt(7)
	v_lshlrev_b32_e32 v77, 16, v77
	v_add_f32_e32 v68, v68, v77
	ds_read_u16 v77, v69 offset:20592
	s_waitcnt lgkmcnt(7)
	v_lshlrev_b32_e32 v70, 16, v70
	v_add_f32_e32 v68, v68, v70
	ds_read_u16 v70, v69 offset:21120
	s_waitcnt lgkmcnt(7)
	v_lshlrev_b32_e32 v71, 16, v71
	v_add_f32_e32 v68, v68, v71
	ds_read_u16 v71, v69 offset:21648
	s_waitcnt lgkmcnt(7)
	v_lshlrev_b32_e32 v72, 16, v72
	v_add_f32_e32 v68, v68, v72
	ds_read_u16 v72, v69 offset:22176
	s_waitcnt lgkmcnt(7)
	v_lshlrev_b32_e32 v73, 16, v73
	v_add_f32_e32 v68, v68, v73
	ds_read_u16 v73, v69 offset:22704
	s_waitcnt lgkmcnt(7)
	v_lshlrev_b32_e32 v74, 16, v74
	v_add_f32_e32 v68, v68, v74
	ds_read_u16 v74, v69 offset:23232
	s_waitcnt lgkmcnt(7)
	v_lshlrev_b32_e32 v75, 16, v75
	v_add_f32_e32 v68, v68, v75
	ds_read_u16 v75, v69 offset:23760
	s_waitcnt lgkmcnt(7)
	v_lshlrev_b32_e32 v76, 16, v76
	v_add_f32_e32 v68, v68, v76
	ds_read_u16 v76, v69 offset:24288
	s_waitcnt lgkmcnt(7)
	v_lshlrev_b32_e32 v77, 16, v77
	v_add_f32_e32 v68, v68, v77
	ds_read_u16 v77, v69 offset:24816
	s_waitcnt lgkmcnt(7)
	v_lshlrev_b32_e32 v70, 16, v70
	v_add_f32_e32 v68, v68, v70
	ds_read_u16 v70, v69 offset:25344
	s_waitcnt lgkmcnt(7)
	v_lshlrev_b32_e32 v71, 16, v71
	v_add_f32_e32 v68, v68, v71
	ds_read_u16 v71, v69 offset:25872
	s_waitcnt lgkmcnt(7)
	v_lshlrev_b32_e32 v72, 16, v72
	v_add_f32_e32 v68, v68, v72
	ds_read_u16 v72, v69 offset:26400
	s_waitcnt lgkmcnt(7)
	v_lshlrev_b32_e32 v73, 16, v73
	v_add_f32_e32 v68, v68, v73
	ds_read_u16 v73, v69 offset:26928
	s_waitcnt lgkmcnt(7)
	v_lshlrev_b32_e32 v74, 16, v74
	v_add_f32_e32 v68, v68, v74
	ds_read_u16 v74, v69 offset:27456
	s_waitcnt lgkmcnt(7)
	v_lshlrev_b32_e32 v75, 16, v75
	v_add_f32_e32 v68, v68, v75
	ds_read_u16 v75, v69 offset:27984
	s_waitcnt lgkmcnt(7)
	v_lshlrev_b32_e32 v76, 16, v76
	v_add_f32_e32 v68, v68, v76
	ds_read_u16 v76, v69 offset:28512
	s_waitcnt lgkmcnt(7)
	v_lshlrev_b32_e32 v77, 16, v77
	v_add_f32_e32 v68, v68, v77
	ds_read_u16 v77, v69 offset:29040
	s_waitcnt lgkmcnt(7)
	v_lshlrev_b32_e32 v70, 16, v70
	v_add_f32_e32 v68, v68, v70
	ds_read_u16 v70, v69 offset:29568
	s_waitcnt lgkmcnt(7)
	v_lshlrev_b32_e32 v71, 16, v71
	v_add_f32_e32 v68, v68, v71
	ds_read_u16 v71, v69 offset:30096
	s_waitcnt lgkmcnt(7)
	v_lshlrev_b32_e32 v72, 16, v72
	v_add_f32_e32 v68, v68, v72
	ds_read_u16 v72, v69 offset:30624
	s_waitcnt lgkmcnt(7)
	v_lshlrev_b32_e32 v73, 16, v73
	v_add_f32_e32 v68, v68, v73
	ds_read_u16 v73, v69 offset:31152
	s_waitcnt lgkmcnt(7)
	v_lshlrev_b32_e32 v74, 16, v74
	v_add_f32_e32 v68, v68, v74
	ds_read_u16 v74, v69 offset:31680
	s_waitcnt lgkmcnt(7)
	v_lshlrev_b32_e32 v75, 16, v75
	v_add_f32_e32 v68, v68, v75
	ds_read_u16 v75, v69 offset:32208
	s_waitcnt lgkmcnt(7)
	v_lshlrev_b32_e32 v76, 16, v76
	v_add_f32_e32 v68, v68, v76
	ds_read_u16 v76, v69 offset:32736
	s_waitcnt lgkmcnt(7)
	v_lshlrev_b32_e32 v77, 16, v77
	v_add_f32_e32 v68, v68, v77
	ds_read_u16 v77, v69 offset:33264
	s_waitcnt lgkmcnt(7)
	v_lshlrev_b32_e32 v70, 16, v70
	v_add_f32_e32 v68, v68, v70
	s_waitcnt lgkmcnt(6)
	v_lshlrev_b32_e32 v71, 16, v71
	v_add_f32_e32 v68, v68, v71
	s_waitcnt lgkmcnt(5)
	v_lshlrev_b32_e32 v72, 16, v72
	v_add_f32_e32 v68, v68, v72
	s_waitcnt lgkmcnt(4)
	v_lshlrev_b32_e32 v73, 16, v73
	v_add_f32_e32 v68, v68, v73
	s_waitcnt lgkmcnt(3)
	v_lshlrev_b32_e32 v74, 16, v74
	v_add_f32_e32 v68, v68, v74
	s_waitcnt lgkmcnt(2)
	v_lshlrev_b32_e32 v75, 16, v75
	v_add_f32_e32 v68, v68, v75
	s_waitcnt lgkmcnt(1)
	v_lshlrev_b32_e32 v76, 16, v76
	v_add_f32_e32 v68, v68, v76
	s_waitcnt lgkmcnt(0)
	v_lshlrev_b32_e32 v77, 16, v77
	v_add_f32_e32 v68, v68, v77
	ds_read_b32 v69, v133 offset:1536
	s_waitcnt lgkmcnt(0)
	v_fmac_f32_e32 v68, v0, v69
	ds_write_b32 v133, v68 offset:1536

; __device__ __forceinline__ unsigned pk2hw(float lo, float hi) { unsigned r; asm("s_nop 1\n\tv_cvt_pk_bf16_f32 %0, %1, %2" : "=v"(r) : "v"(lo), "v"(hi)); return r; }
; __device__ __forceinline__ float sigmoidf_(float x) { return __builtin_amdgcn_rcpf(1.f + __expf(-x)); }
;     __device__ __forceinline__ void operator()(const f32x4 (&acc)[2][2][4][2], const Unit& u, int wr, int wc, int fr, int fq) const {
;     ...
;             for (int m = 0; m < 4; ++m) { const int row = row0 + ai * 128 + m * 16;
; #pragma unroll
;                 for (int bj = 0; bj < 2; ++bj) { const int col = col0 + bj * 128;
;                     const u32x4 gw = *(const u32x4*)(gsrc + (size_t)row * gld + n * D + col);
;                     f32x4 g0 = (f32x4){bflo(gw.x), bfhi(gw.x), bflo(gw.y), bfhi(gw.y)}, g1 = (f32x4){bflo(gw.z), bfhi(gw.z), bflo(gw.w), bfhi(gw.w)};
;                     if (bgate) { const f32x4 b0 = *(const f32x4*)(bgate + n * D + col), b1 = *(const f32x4*)(bgate + n * D + col + 4);
;                         g0[0] = sigmoidf_(g0[0] + b0[0]); g0[1] = sigmoidf_(g0[1] + b0[1]); g0[2] = sigmoidf_(g0[2] + b0[2]); g0[3] = sigmoidf_(g0[3] + b0[3]);
;                         g1[0] = sigmoidf_(g1[0] + b1[0]); g1[1] = sigmoidf_(g1[1] + b1[1]); g1[2] = sigmoidf_(g1[2] + b1[2]); g1[3] = sigmoidf_(g1[3] + b1[3]); }
;                     const f32x4 v0r = acc[ai][bj][m][0] * g0, v1r = acc[ai][bj][m][1] * g1; f32x4 v0 = v0r, v1 = v1r;
;                     bf16_t* mp = merged + (size_t)row * D + col;
;                     if (n > 0) { const u32x4 o = *(const u32x4*)mp; v0[0] += bflo(o.x); v0[1] += bfhi(o.x); v0[2] += bflo(o.y); v0[3] += bfhi(o.y); v1[0] += bflo(o.z); v1[1] += bfhi(o.z); v1[2] += bflo(o.w); v1[3] += bfhi(o.w); }
;                     u32x4 w; w.x = pk2hw(v0[0], v0[1]); w.y = pk2hw(v0[2], v0[3]); w.z = pk2hw(v1[0], v1[1]); w.w = pk2hw(v1[2], v1[3]); *(u32x4*)mp = w; } }
.LBB0_677:
	v_mov_b32_e32 v142, v178
	v_mov_b32_e32 v143, v179
	s_lshl_b32 s1, s1, 8
	s_ashr_i32 s12, s28, 5
	s_and_b32 s1, s1, 0x300
	v_add_u32_e32 v144, s53, v142
	s_or_b32 s1, s1, s48
	s_lshl_b32 s26, s12, 10
	v_mad_i64_i32 v[148:149], s[10:11], s40, v144, 0
	v_lshl_add_u32 v142, v143, 3, s1
	s_ashr_i32 s27, s26, 31
	v_lshl_add_u64 v[148:149], v[148:149], 1, s[22:23]
	v_lshl_add_u64 v[148:149], s[26:27], 1, v[148:149]
	v_ashrrev_i32_e32 v143, 31, v142
	v_lshl_add_u64 v[148:149], v[142:143], 1, v[148:149]
	v_ashrrev_i32_e32 v145, 31, v144
	v_lshlrev_b64 v[166:167], 11, v[144:145]
	v_lshl_add_u64 v[166:167], s[20:21], 0, v[166:167]
	v_lshl_add_u64 v[166:167], v[142:143], 1, v[166:167]
	s_mov_b32 s11, 0
	s_and_b64 vcc, exec, s[8:9]
	s_cbranch_vccz .Leb_nobg_ld
	s_lshl_b64 s[28:29], s[26:27], 2
	v_lshl_add_u64 v[250:251], v[130:131], 0, s[28:29]
	v_lshl_add_u64 v[250:251], v[142:143], 2, v[250:251]
	global_load_dwordx4 v[234:237], v[250:251], off
	global_load_dwordx4 v[238:241], v[250:251], off offset:16
	global_load_dwordx4 v[242:245], v[250:251], off offset:512
	global_load_dwordx4 v[246:249], v[250:251], off offset:528
.Leb_nobg_ld:
	s_mul_i32 s10, s40, 0
	v_lshl_add_u64 v[250:251], s[10:11], 0, v[148:149]
	global_load_dwordx4 v[182:185], v[250:251], off
	s_mov_b32 s10, 0x0
	v_lshl_add_u64 v[250:251], s[10:11], 0, v[166:167]
	global_load_dwordx4 v[186:189], v[250:251], off
	s_mul_i32 s10, s40, 0
	v_lshl_add_u64 v[250:251], s[10:11], 0, v[148:149]
	global_load_dwordx4 v[190:193], v[250:251], off offset:256
	s_mov_b32 s10, 0x0
	v_lshl_add_u64 v[250:251], s[10:11], 0, v[166:167]
	global_load_dwordx4 v[194:197], v[250:251], off offset:256
	s_mul_i32 s10, s40, 32
	v_lshl_add_u64 v[250:251], s[10:11], 0, v[148:149]
	global_load_dwordx4 v[198:201], v[250:251], off
	s_mov_b32 s10, 0x8000
	v_lshl_add_u64 v[250:251], s[10:11], 0, v[166:167]
	global_load_dwordx4 v[202:205], v[250:251], off
	s_mul_i32 s10, s40, 32
	v_lshl_add_u64 v[250:251], s[10:11], 0, v[148:149]
	global_load_dwordx4 v[206:209], v[250:251], off offset:256
	s_mov_b32 s10, 0x8000
	v_lshl_add_u64 v[250:251], s[10:11], 0, v[166:167]
	global_load_dwordx4 v[210:213], v[250:251], off offset:256
	s_mul_i32 s10, s40, 64
	v_lshl_add_u64 v[250:251], s[10:11], 0, v[148:149]
	global_load_dwordx4 v[214:217], v[250:251], off
	s_mov_b32 s10, 0x10000
	v_lshl_add_u64 v[250:251], s[10:11], 0, v[166:167]
	global_load_dwordx4 v[218:221], v[250:251], off
	s_waitcnt vmcnt(8)
	v_lshlrev_b32_e32 v170, 16, v182
	v_and_b32_e32 v171, 0xffff0000, v182
	v_lshlrev_b32_e32 v172, 16, v183
	v_and_b32_e32 v173, 0xffff0000, v183
	v_lshlrev_b32_e32 v174, 16, v184
	v_and_b32_e32 v175, 0xffff0000, v184
	v_lshlrev_b32_e32 v176, 16, v185
	v_and_b32_e32 v177, 0xffff0000, v185
	s_and_b64 vcc, exec, s[8:9]
	s_cbranch_vccz .Leb_nosig_0
	v_add_f32_e32 v170, v234, v170
	v_add_f32_e32 v171, v235, v171
	v_add_f32_e32 v172, v236, v172
	v_add_f32_e32 v173, v237, v173
	v_add_f32_e32 v174, v238, v174
	v_add_f32_e32 v175, v239, v175
	v_add_f32_e32 v176, v240, v176
	v_add_f32_e32 v177, v241, v177
	v_mul_f32_e32 v170, 0xbfb8aa3b, v170
	v_mul_f32_e32 v171, 0xbfb8aa3b, v171
	v_mul_f32_e32 v172, 0xbfb8aa3b, v172
	v_mul_f32_e32 v173, 0xbfb8aa3b, v173
	v_mul_f32_e32 v174, 0xbfb8aa3b, v174
	v_mul_f32_e32 v175, 0xbfb8aa3b, v175
	v_mul_f32_e32 v176, 0xbfb8aa3b, v176
	v_mul_f32_e32 v177, 0xbfb8aa3b, v177
	v_exp_f32_e32 v170, v170
	v_exp_f32_e32 v171, v171
	v_exp_f32_e32 v172, v172
	v_exp_f32_e32 v173, v173
	v_exp_f32_e32 v174, v174
	v_exp_f32_e32 v175, v175
	v_exp_f32_e32 v176, v176
	v_exp_f32_e32 v177, v177
	s_nop 0
	v_add_f32_e32 v170, 1.0, v170
	v_add_f32_e32 v171, 1.0, v171
	v_add_f32_e32 v172, 1.0, v172
	v_add_f32_e32 v173, 1.0, v173
	v_add_f32_e32 v174, 1.0, v174
	v_add_f32_e32 v175, 1.0, v175
	v_add_f32_e32 v176, 1.0, v176
	v_add_f32_e32 v177, 1.0, v177
	v_rcp_f32_e32 v170, v170
	v_rcp_f32_e32 v171, v171
	v_rcp_f32_e32 v172, v172
	v_rcp_f32_e32 v173, v173
	v_rcp_f32_e32 v174, v174
	v_rcp_f32_e32 v175, v175
	v_rcp_f32_e32 v176, v176
	v_rcp_f32_e32 v177, v177
	s_nop 0
.Leb_nosig_0:
	v_pk_mul_f32 v[126:127], v[126:127], v[170:171]
	v_pk_mul_f32 v[128:129], v[128:129], v[172:173]
	v_pk_mul_f32 v[122:123], v[122:123], v[174:175]
	v_pk_mul_f32 v[124:125], v[124:125], v[176:177]
	s_cmp_lt_i32 s12, 1
	s_cbranch_scc1 .Leb_noadd_0
	v_lshlrev_b32_e32 v170, 16, v186
	v_and_b32_e32 v171, 0xffff0000, v186
	v_lshlrev_b32_e32 v172, 16, v187
	v_and_b32_e32 v173, 0xffff0000, v187
	v_lshlrev_b32_e32 v174, 16, v188
	v_and_b32_e32 v175, 0xffff0000, v188
	v_lshlrev_b32_e32 v176, 16, v189
	v_and_b32_e32 v177, 0xffff0000, v189
	v_pk_add_f32 v[126:127], v[126:127], v[170:171]
	v_pk_add_f32 v[128:129], v[128:129], v[172:173]
	v_pk_add_f32 v[122:123], v[122:123], v[174:175]
	v_pk_add_f32 v[124:125], v[124:125], v[176:177]
; __device__ __forceinline__ unsigned pk2hw(float lo, float hi) { unsigned r; asm("s_nop 1\n\tv_cvt_pk_bf16_f32 %0, %1, %2" : "=v"(r) : "v"(lo), "v"(hi)); return r; }
; __device__ __forceinline__ float sigmoidf_(float x) { return __builtin_amdgcn_rcpf(1.f + __expf(-x)); }
;     __device__ __forceinline__ void operator()(const f32x4 (&acc)[2][2][4][2], const Unit& u, int wr, int wc, int fr, int fq) const {
;     ...
;             for (int m = 0; m < 4; ++m) { const int row = row0 + ai * 128 + m * 16;
; #pragma unroll
;                 for (int bj = 0; bj < 2; ++bj) { const int col = col0 + bj * 128;
;                     const u32x4 gw = *(const u32x4*)(gsrc + (size_t)row * gld + n * D + col);
;                     f32x4 g0 = (f32x4){bflo(gw.x), bfhi(gw.x), bflo(gw.y), bfhi(gw.y)}, g1 = (f32x4){bflo(gw.z), bfhi(gw.z), bflo(gw.w), bfhi(gw.w)};
;                     if (bgate) { const f32x4 b0 = *(const f32x4*)(bgate + n * D + col), b1 = *(const f32x4*)(bgate + n * D + col + 4);
;                         g0[0] = sigmoidf_(g0[0] + b0[0]); g0[1] = sigmoidf_(g0[1] + b0[1]); g0[2] = sigmoidf_(g0[2] + b0[2]); g0[3] = sigmoidf_(g0[3] + b0[3]);
;                         g1[0] = sigmoidf_(g1[0] + b1[0]); g1[1] = sigmoidf_(g1[1] + b1[1]); g1[2] = sigmoidf_(g1[2] + b1[2]); g1[3] = sigmoidf_(g1[3] + b1[3]); }
;                     const f32x4 v0r = acc[ai][bj][m][0] * g0, v1r = acc[ai][bj][m][1] * g1; f32x4 v0 = v0r, v1 = v1r;
;                     bf16_t* mp = merged + (size_t)row * D + col;
;                     if (n > 0) { const u32x4 o = *(const u32x4*)mp; v0[0] += bflo(o.x); v0[1] += bfhi(o.x); v0[2] += bflo(o.y); v0[3] += bfhi(o.y); v1[0] += bflo(o.z); v1[1] += bfhi(o.z); v1[2] += bflo(o.w); v1[3] += bfhi(o.w); }
;                     u32x4 w; w.x = pk2hw(v0[0], v0[1]); w.y = pk2hw(v0[2], v0[3]); w.z = pk2hw(v1[0], v1[1]); w.w = pk2hw(v1[2], v1[3]); *(u32x4*)mp = w; } }
.Leb_noadd_0:
	s_nop 1
	v_cvt_pk_bf16_f32 v126, v126, v127
	v_cvt_pk_bf16_f32 v127, v128, v129
	v_cvt_pk_bf16_f32 v128, v122, v123
	v_cvt_pk_bf16_f32 v129, v124, v125
	s_mov_b32 s10, 0x0
	v_lshl_add_u64 v[250:251], s[10:11], 0, v[166:167]
	global_store_dwordx4 v[250:251], v[126:129], off
	s_mul_i32 s10, s40, 64
	v_lshl_add_u64 v[250:251], s[10:11], 0, v[148:149]
	global_load_dwordx4 v[122:125], v[250:251], off offset:256
	s_mov_b32 s10, 0x10000
	v_lshl_add_u64 v[250:251], s[10:11], 0, v[166:167]
	global_load_dwordx4 v[126:129], v[250:251], off offset:256
	s_waitcnt vmcnt(9)
	v_lshlrev_b32_e32 v170, 16, v190
	v_and_b32_e32 v171, 0xffff0000, v190
	v_lshlrev_b32_e32 v172, 16, v191
	v_and_b32_e32 v173, 0xffff0000, v191
	v_lshlrev_b32_e32 v174, 16, v192
	v_and_b32_e32 v175, 0xffff0000, v192
	v_lshlrev_b32_e32 v176, 16, v193
	v_and_b32_e32 v177, 0xffff0000, v193
	s_and_b64 vcc, exec, s[8:9]
	s_cbranch_vccz .Leb_nosig_1
	v_add_f32_e32 v170, v242, v170
	v_add_f32_e32 v171, v243, v171
	v_add_f32_e32 v172, v244, v172
	v_add_f32_e32 v173, v245, v173
	v_add_f32_e32 v174, v246, v174
	v_add_f32_e32 v175, v247, v175
	v_add_f32_e32 v176, v248, v176
	v_add_f32_e32 v177, v249, v177
	v_mul_f32_e32 v170, 0xbfb8aa3b, v170
	v_mul_f32_e32 v171, 0xbfb8aa3b, v171
	v_mul_f32_e32 v172, 0xbfb8aa3b, v172
	v_mul_f32_e32 v173, 0xbfb8aa3b, v173
	v_mul_f32_e32 v174, 0xbfb8aa3b, v174
	v_mul_f32_e32 v175, 0xbfb8aa3b, v175
	v_mul_f32_e32 v176, 0xbfb8aa3b, v176
	v_mul_f32_e32 v177, 0xbfb8aa3b, v177
	v_exp_f32_e32 v170, v170
	v_exp_f32_e32 v171, v171
	v_exp_f32_e32 v172, v172
	v_exp_f32_e32 v173, v173
	v_exp_f32_e32 v174, v174
	v_exp_f32_e32 v175, v175
	v_exp_f32_e32 v176, v176
	v_exp_f32_e32 v177, v177
	s_nop 0
	v_add_f32_e32 v170, 1.0, v170
	v_add_f32_e32 v171, 1.0, v171
	v_add_f32_e32 v172, 1.0, v172
	v_add_f32_e32 v173, 1.0, v173
	v_add_f32_e32 v174, 1.0, v174
	v_add_f32_e32 v175, 1.0, v175
	v_add_f32_e32 v176, 1.0, v176
	v_add_f32_e32 v177, 1.0, v177
	v_rcp_f32_e32 v170, v170
	v_rcp_f32_e32 v171, v171
	v_rcp_f32_e32 v172, v172
	v_rcp_f32_e32 v173, v173
	v_rcp_f32_e32 v174, v174
	v_rcp_f32_e32 v175, v175
	v_rcp_f32_e32 v176, v176
	v_rcp_f32_e32 v177, v177
	s_nop 0
.Leb_nosig_1:
	v_pk_mul_f32 v[118:119], v[118:119], v[170:171]
	v_pk_mul_f32 v[120:121], v[120:121], v[172:173]
	v_pk_mul_f32 v[114:115], v[114:115], v[174:175]
	v_pk_mul_f32 v[116:117], v[116:117], v[176:177]
	s_cmp_lt_i32 s12, 1
	s_cbranch_scc1 .Leb_noadd_1
	v_lshlrev_b32_e32 v170, 16, v194
	v_and_b32_e32 v171, 0xffff0000, v194
	v_lshlrev_b32_e32 v172, 16, v195
	v_and_b32_e32 v173, 0xffff0000, v195
	v_lshlrev_b32_e32 v174, 16, v196
	v_and_b32_e32 v175, 0xffff0000, v196
	v_lshlrev_b32_e32 v176, 16, v197
	v_and_b32_e32 v177, 0xffff0000, v197
	v_pk_add_f32 v[118:119], v[118:119], v[170:171]
	v_pk_add_f32 v[120:121], v[120:121], v[172:173]
	v_pk_add_f32 v[114:115], v[114:115], v[174:175]
	v_pk_add_f32 v[116:117], v[116:117], v[176:177]
.Leb_noadd_1:
	s_nop 1
	v_cvt_pk_bf16_f32 v118, v118, v119
	v_cvt_pk_bf16_f32 v119, v120, v121
	v_cvt_pk_bf16_f32 v120, v114, v115
	v_cvt_pk_bf16_f32 v121, v116, v117
	s_mov_b32 s10, 0x0
	v_lshl_add_u64 v[250:251], s[10:11], 0, v[166:167]
	global_store_dwordx4 v[250:251], v[118:121], off offset:256
	s_mul_i32 s10, s40, 96
	v_lshl_add_u64 v[250:251], s[10:11], 0, v[148:149]
	global_load_dwordx4 v[114:117], v[250:251], off
	s_mov_b32 s10, 0x18000
	v_lshl_add_u64 v[250:251], s[10:11], 0, v[166:167]
	global_load_dwordx4 v[118:121], v[250:251], off
	s_waitcnt vmcnt(10)
	v_lshlrev_b32_e32 v170, 16, v198
	v_and_b32_e32 v171, 0xffff0000, v198
	v_lshlrev_b32_e32 v172, 16, v199
	v_and_b32_e32 v173, 0xffff0000, v199
	v_lshlrev_b32_e32 v174, 16, v200
	v_and_b32_e32 v175, 0xffff0000, v200
	v_lshlrev_b32_e32 v176, 16, v201
	v_and_b32_e32 v177, 0xffff0000, v201
	s_and_b64 vcc, exec, s[8:9]
	s_cbranch_vccz .Leb_nosig_2
	v_add_f32_e32 v170, v234, v170
	v_add_f32_e32 v171, v235, v171
	v_add_f32_e32 v172, v236, v172
	v_add_f32_e32 v173, v237, v173
	v_add_f32_e32 v174, v238, v174
	v_add_f32_e32 v175, v239, v175
	v_add_f32_e32 v176, v240, v176
	v_add_f32_e32 v177, v241, v177
	v_mul_f32_e32 v170, 0xbfb8aa3b, v170
	v_mul_f32_e32 v171, 0xbfb8aa3b, v171
	v_mul_f32_e32 v172, 0xbfb8aa3b, v172
	v_mul_f32_e32 v173, 0xbfb8aa3b, v173
	v_mul_f32_e32 v174, 0xbfb8aa3b, v174
	v_mul_f32_e32 v175, 0xbfb8aa3b, v175
	v_mul_f32_e32 v176, 0xbfb8aa3b, v176
	v_mul_f32_e32 v177, 0xbfb8aa3b, v177
	v_exp_f32_e32 v170, v170
	v_exp_f32_e32 v171, v171
	v_exp_f32_e32 v172, v172
	v_exp_f32_e32 v173, v173
	v_exp_f32_e32 v174, v174
	v_exp_f32_e32 v175, v175
	v_exp_f32_e32 v176, v176
	v_exp_f32_e32 v177, v177
	s_nop 0
	v_add_f32_e32 v170, 1.0, v170
	v_add_f32_e32 v171, 1.0, v171
	v_add_f32_e32 v172, 1.0, v172
	v_add_f32_e32 v173, 1.0, v173
	v_add_f32_e32 v174, 1.0, v174
	v_add_f32_e32 v175, 1.0, v175
	v_add_f32_e32 v176, 1.0, v176
	v_add_f32_e32 v177, 1.0, v177
	v_rcp_f32_e32 v170, v170
	v_rcp_f32_e32 v171, v171
	v_rcp_f32_e32 v172, v172
	v_rcp_f32_e32 v173, v173
	v_rcp_f32_e32 v174, v174
	v_rcp_f32_e32 v175, v175
	v_rcp_f32_e32 v176, v176
	v_rcp_f32_e32 v177, v177
	s_nop 0
.Leb_nosig_2:
	v_pk_mul_f32 v[110:111], v[110:111], v[170:171]
	v_pk_mul_f32 v[112:113], v[112:113], v[172:173]
	v_pk_mul_f32 v[106:107], v[106:107], v[174:175]
	v_pk_mul_f32 v[108:109], v[108:109], v[176:177]
	s_cmp_lt_i32 s12, 1
	s_cbranch_scc1 .Leb_noadd_2
	v_lshlrev_b32_e32 v170, 16, v202
	v_and_b32_e32 v171, 0xffff0000, v202
	v_lshlrev_b32_e32 v172, 16, v203
	v_and_b32_e32 v173, 0xffff0000, v203
	v_lshlrev_b32_e32 v174, 16, v204
	v_and_b32_e32 v175, 0xffff0000, v204
	v_lshlrev_b32_e32 v176, 16, v205
	v_and_b32_e32 v177, 0xffff0000, v205
	v_pk_add_f32 v[110:111], v[110:111], v[170:171]
	v_pk_add_f32 v[112:113], v[112:113], v[172:173]
	v_pk_add_f32 v[106:107], v[106:107], v[174:175]
	v_pk_add_f32 v[108:109], v[108:109], v[176:177]
; __device__ __forceinline__ unsigned pk2hw(float lo, float hi) { unsigned r; asm("s_nop 1\n\tv_cvt_pk_bf16_f32 %0, %1, %2" : "=v"(r) : "v"(lo), "v"(hi)); return r; }
; __device__ __forceinline__ float sigmoidf_(float x) { return __builtin_amdgcn_rcpf(1.f + __expf(-x)); }
;     __device__ __forceinline__ void operator()(const f32x4 (&acc)[2][2][4][2], const Unit& u, int wr, int wc, int fr, int fq) const {
;     ...
;             for (int m = 0; m < 4; ++m) { const int row = row0 + ai * 128 + m * 16;
; #pragma unroll
;                 for (int bj = 0; bj < 2; ++bj) { const int col = col0 + bj * 128;
;                     const u32x4 gw = *(const u32x4*)(gsrc + (size_t)row * gld + n * D + col);
;                     f32x4 g0 = (f32x4){bflo(gw.x), bfhi(gw.x), bflo(gw.y), bfhi(gw.y)}, g1 = (f32x4){bflo(gw.z), bfhi(gw.z), bflo(gw.w), bfhi(gw.w)};
;                     if (bgate) { const f32x4 b0 = *(const f32x4*)(bgate + n * D + col), b1 = *(const f32x4*)(bgate + n * D + col + 4);
;                         g0[0] = sigmoidf_(g0[0] + b0[0]); g0[1] = sigmoidf_(g0[1] + b0[1]); g0[2] = sigmoidf_(g0[2] + b0[2]); g0[3] = sigmoidf_(g0[3] + b0[3]);
;                         g1[0] = sigmoidf_(g1[0] + b1[0]); g1[1] = sigmoidf_(g1[1] + b1[1]); g1[2] = sigmoidf_(g1[2] + b1[2]); g1[3] = sigmoidf_(g1[3] + b1[3]); }
;                     const f32x4 v0r = acc[ai][bj][m][0] * g0, v1r = acc[ai][bj][m][1] * g1; f32x4 v0 = v0r, v1 = v1r;
;                     bf16_t* mp = merged + (size_t)row * D + col;
;                     if (n > 0) { const u32x4 o = *(const u32x4*)mp; v0[0] += bflo(o.x); v0[1] += bfhi(o.x); v0[2] += bflo(o.y); v0[3] += bfhi(o.y); v1[0] += bflo(o.z); v1[1] += bfhi(o.z); v1[2] += bflo(o.w); v1[3] += bfhi(o.w); }
;                     u32x4 w; w.x = pk2hw(v0[0], v0[1]); w.y = pk2hw(v0[2], v0[3]); w.z = pk2hw(v1[0], v1[1]); w.w = pk2hw(v1[2], v1[3]); *(u32x4*)mp = w; } }
.Leb_noadd_2:
	s_nop 1
	v_cvt_pk_bf16_f32 v110, v110, v111
	v_cvt_pk_bf16_f32 v111, v112, v113
	v_cvt_pk_bf16_f32 v112, v106, v107
	v_cvt_pk_bf16_f32 v113, v108, v109
	s_mov_b32 s10, 0x8000
	v_lshl_add_u64 v[250:251], s[10:11], 0, v[166:167]
	global_store_dwordx4 v[250:251], v[110:113], off
	s_mul_i32 s10, s40, 96
	v_lshl_add_u64 v[250:251], s[10:11], 0, v[148:149]
	global_load_dwordx4 v[106:109], v[250:251], off offset:256
	s_mov_b32 s10, 0x18000
	v_lshl_add_u64 v[250:251], s[10:11], 0, v[166:167]
	global_load_dwordx4 v[110:113], v[250:251], off offset:256
	s_waitcnt vmcnt(11)
	v_lshlrev_b32_e32 v170, 16, v206
	v_and_b32_e32 v171, 0xffff0000, v206
	v_lshlrev_b32_e32 v172, 16, v207
	v_and_b32_e32 v173, 0xffff0000, v207
	v_lshlrev_b32_e32 v174, 16, v208
	v_and_b32_e32 v175, 0xffff0000, v208
	v_lshlrev_b32_e32 v176, 16, v209
	v_and_b32_e32 v177, 0xffff0000, v209
	s_and_b64 vcc, exec, s[8:9]
	s_cbranch_vccz .Leb_nosig_3
	v_add_f32_e32 v170, v242, v170
	v_add_f32_e32 v171, v243, v171
	v_add_f32_e32 v172, v244, v172
	v_add_f32_e32 v173, v245, v173
	v_add_f32_e32 v174, v246, v174
	v_add_f32_e32 v175, v247, v175
	v_add_f32_e32 v176, v248, v176
	v_add_f32_e32 v177, v249, v177
	v_mul_f32_e32 v170, 0xbfb8aa3b, v170
	v_mul_f32_e32 v171, 0xbfb8aa3b, v171
	v_mul_f32_e32 v172, 0xbfb8aa3b, v172
	v_mul_f32_e32 v173, 0xbfb8aa3b, v173
	v_mul_f32_e32 v174, 0xbfb8aa3b, v174
	v_mul_f32_e32 v175, 0xbfb8aa3b, v175
	v_mul_f32_e32 v176, 0xbfb8aa3b, v176
	v_mul_f32_e32 v177, 0xbfb8aa3b, v177
	v_exp_f32_e32 v170, v170
	v_exp_f32_e32 v171, v171
	v_exp_f32_e32 v172, v172
	v_exp_f32_e32 v173, v173
	v_exp_f32_e32 v174, v174
	v_exp_f32_e32 v175, v175
	v_exp_f32_e32 v176, v176
	v_exp_f32_e32 v177, v177
	s_nop 0
	v_add_f32_e32 v170, 1.0, v170
	v_add_f32_e32 v171, 1.0, v171
	v_add_f32_e32 v172, 1.0, v172
	v_add_f32_e32 v173, 1.0, v173
	v_add_f32_e32 v174, 1.0, v174
	v_add_f32_e32 v175, 1.0, v175
	v_add_f32_e32 v176, 1.0, v176
	v_add_f32_e32 v177, 1.0, v177
	v_rcp_f32_e32 v170, v170
	v_rcp_f32_e32 v171, v171
	v_rcp_f32_e32 v172, v172
	v_rcp_f32_e32 v173, v173
	v_rcp_f32_e32 v174, v174
	v_rcp_f32_e32 v175, v175
	v_rcp_f32_e32 v176, v176
	v_rcp_f32_e32 v177, v177
	s_nop 0
.Leb_nosig_3:
	v_pk_mul_f32 v[102:103], v[102:103], v[170:171]
	v_pk_mul_f32 v[104:105], v[104:105], v[172:173]
	v_pk_mul_f32 v[98:99], v[98:99], v[174:175]
	v_pk_mul_f32 v[100:101], v[100:101], v[176:177]
	s_cmp_lt_i32 s12, 1
	s_cbranch_scc1 .Leb_noadd_3
	v_lshlrev_b32_e32 v170, 16, v210
	v_and_b32_e32 v171, 0xffff0000, v210
	v_lshlrev_b32_e32 v172, 16, v211
	v_and_b32_e32 v173, 0xffff0000, v211
	v_lshlrev_b32_e32 v174, 16, v212
	v_and_b32_e32 v175, 0xffff0000, v212
	v_lshlrev_b32_e32 v176, 16, v213
	v_and_b32_e32 v177, 0xffff0000, v213
	v_pk_add_f32 v[102:103], v[102:103], v[170:171]
	v_pk_add_f32 v[104:105], v[104:105], v[172:173]
	v_pk_add_f32 v[98:99], v[98:99], v[174:175]
	v_pk_add_f32 v[100:101], v[100:101], v[176:177]
.Leb_noadd_3:
	s_nop 1
	v_cvt_pk_bf16_f32 v102, v102, v103
	v_cvt_pk_bf16_f32 v103, v104, v105
	v_cvt_pk_bf16_f32 v104, v98, v99
	v_cvt_pk_bf16_f32 v105, v100, v101
	s_mov_b32 s10, 0x8000
	v_lshl_add_u64 v[250:251], s[10:11], 0, v[166:167]
	global_store_dwordx4 v[250:251], v[102:105], off offset:256
	s_mul_i32 s10, s40, 256
	v_lshl_add_u64 v[250:251], s[10:11], 0, v[148:149]
	global_load_dwordx4 v[98:101], v[250:251], off
	s_mov_b32 s10, 0x40000
	v_lshl_add_u64 v[250:251], s[10:11], 0, v[166:167]
	global_load_dwordx4 v[102:105], v[250:251], off
	s_waitcnt vmcnt(12)
	v_lshlrev_b32_e32 v170, 16, v214
	v_and_b32_e32 v171, 0xffff0000, v214
	v_lshlrev_b32_e32 v172, 16, v215
	v_and_b32_e32 v173, 0xffff0000, v215
	v_lshlrev_b32_e32 v174, 16, v216
	v_and_b32_e32 v175, 0xffff0000, v216
	v_lshlrev_b32_e32 v176, 16, v217
	v_and_b32_e32 v177, 0xffff0000, v217
	s_and_b64 vcc, exec, s[8:9]
	s_cbranch_vccz .Leb_nosig_4
	v_add_f32_e32 v170, v234, v170
	v_add_f32_e32 v171, v235, v171
	v_add_f32_e32 v172, v236, v172
	v_add_f32_e32 v173, v237, v173
	v_add_f32_e32 v174, v238, v174
	v_add_f32_e32 v175, v239, v175
	v_add_f32_e32 v176, v240, v176
	v_add_f32_e32 v177, v241, v177
	v_mul_f32_e32 v170, 0xbfb8aa3b, v170
	v_mul_f32_e32 v171, 0xbfb8aa3b, v171
	v_mul_f32_e32 v172, 0xbfb8aa3b, v172
	v_mul_f32_e32 v173, 0xbfb8aa3b, v173
	v_mul_f32_e32 v174, 0xbfb8aa3b, v174
	v_mul_f32_e32 v175, 0xbfb8aa3b, v175
	v_mul_f32_e32 v176, 0xbfb8aa3b, v176
	v_mul_f32_e32 v177, 0xbfb8aa3b, v177
	v_exp_f32_e32 v170, v170
	v_exp_f32_e32 v171, v171
	v_exp_f32_e32 v172, v172
	v_exp_f32_e32 v173, v173
	v_exp_f32_e32 v174, v174
	v_exp_f32_e32 v175, v175
	v_exp_f32_e32 v176, v176
	v_exp_f32_e32 v177, v177
	s_nop 0
	v_add_f32_e32 v170, 1.0, v170
	v_add_f32_e32 v171, 1.0, v171
	v_add_f32_e32 v172, 1.0, v172
	v_add_f32_e32 v173, 1.0, v173
	v_add_f32_e32 v174, 1.0, v174
	v_add_f32_e32 v175, 1.0, v175
	v_add_f32_e32 v176, 1.0, v176
	v_add_f32_e32 v177, 1.0, v177
	v_rcp_f32_e32 v170, v170
	v_rcp_f32_e32 v171, v171
	v_rcp_f32_e32 v172, v172
	v_rcp_f32_e32 v173, v173
	v_rcp_f32_e32 v174, v174
	v_rcp_f32_e32 v175, v175
	v_rcp_f32_e32 v176, v176
	v_rcp_f32_e32 v177, v177
	s_nop 0
.Leb_nosig_4:
	v_pk_mul_f32 v[94:95], v[94:95], v[170:171]
	v_pk_mul_f32 v[96:97], v[96:97], v[172:173]
	v_pk_mul_f32 v[90:91], v[90:91], v[174:175]
	v_pk_mul_f32 v[92:93], v[92:93], v[176:177]
	s_cmp_lt_i32 s12, 1
	s_cbranch_scc1 .Leb_noadd_4
	v_lshlrev_b32_e32 v170, 16, v218
	v_and_b32_e32 v171, 0xffff0000, v218
	v_lshlrev_b32_e32 v172, 16, v219
	v_and_b32_e32 v173, 0xffff0000, v219
	v_lshlrev_b32_e32 v174, 16, v220
	v_and_b32_e32 v175, 0xffff0000, v220
	v_lshlrev_b32_e32 v176, 16, v221
	v_and_b32_e32 v177, 0xffff0000, v221
	v_pk_add_f32 v[94:95], v[94:95], v[170:171]
	v_pk_add_f32 v[96:97], v[96:97], v[172:173]
	v_pk_add_f32 v[90:91], v[90:91], v[174:175]
	v_pk_add_f32 v[92:93], v[92:93], v[176:177]
; __device__ __forceinline__ unsigned pk2hw(float lo, float hi) { unsigned r; asm("s_nop 1\n\tv_cvt_pk_bf16_f32 %0, %1, %2" : "=v"(r) : "v"(lo), "v"(hi)); return r; }
; __device__ __forceinline__ float sigmoidf_(float x) { return __builtin_amdgcn_rcpf(1.f + __expf(-x)); }
;     __device__ __forceinline__ void operator()(const f32x4 (&acc)[2][2][4][2], const Unit& u, int wr, int wc, int fr, int fq) const {
;     ...
;             for (int m = 0; m < 4; ++m) { const int row = row0 + ai * 128 + m * 16;
; #pragma unroll
;                 for (int bj = 0; bj < 2; ++bj) { const int col = col0 + bj * 128;
;                     const u32x4 gw = *(const u32x4*)(gsrc + (size_t)row * gld + n * D + col);
;                     f32x4 g0 = (f32x4){bflo(gw.x), bfhi(gw.x), bflo(gw.y), bfhi(gw.y)}, g1 = (f32x4){bflo(gw.z), bfhi(gw.z), bflo(gw.w), bfhi(gw.w)};
;                     if (bgate) { const f32x4 b0 = *(const f32x4*)(bgate + n * D + col), b1 = *(const f32x4*)(bgate + n * D + col + 4);
;                         g0[0] = sigmoidf_(g0[0] + b0[0]); g0[1] = sigmoidf_(g0[1] + b0[1]); g0[2] = sigmoidf_(g0[2] + b0[2]); g0[3] = sigmoidf_(g0[3] + b0[3]);
;                         g1[0] = sigmoidf_(g1[0] + b1[0]); g1[1] = sigmoidf_(g1[1] + b1[1]); g1[2] = sigmoidf_(g1[2] + b1[2]); g1[3] = sigmoidf_(g1[3] + b1[3]); }
;                     const f32x4 v0r = acc[ai][bj][m][0] * g0, v1r = acc[ai][bj][m][1] * g1; f32x4 v0 = v0r, v1 = v1r;
;                     bf16_t* mp = merged + (size_t)row * D + col;
;                     if (n > 0) { const u32x4 o = *(const u32x4*)mp; v0[0] += bflo(o.x); v0[1] += bfhi(o.x); v0[2] += bflo(o.y); v0[3] += bfhi(o.y); v1[0] += bflo(o.z); v1[1] += bfhi(o.z); v1[2] += bflo(o.w); v1[3] += bfhi(o.w); }
;                     u32x4 w; w.x = pk2hw(v0[0], v0[1]); w.y = pk2hw(v0[2], v0[3]); w.z = pk2hw(v1[0], v1[1]); w.w = pk2hw(v1[2], v1[3]); *(u32x4*)mp = w; } }
.Leb_noadd_4:
	s_nop 1
	v_cvt_pk_bf16_f32 v94, v94, v95
	v_cvt_pk_bf16_f32 v95, v96, v97
	v_cvt_pk_bf16_f32 v96, v90, v91
	v_cvt_pk_bf16_f32 v97, v92, v93
	s_mov_b32 s10, 0x10000
	v_lshl_add_u64 v[250:251], s[10:11], 0, v[166:167]
	global_store_dwordx4 v[250:251], v[94:97], off
	s_mul_i32 s10, s40, 256
	v_lshl_add_u64 v[250:251], s[10:11], 0, v[148:149]
	global_load_dwordx4 v[90:93], v[250:251], off offset:256
	s_mov_b32 s10, 0x40000
	v_lshl_add_u64 v[250:251], s[10:11], 0, v[166:167]
	global_load_dwordx4 v[94:97], v[250:251], off offset:256
	s_waitcnt vmcnt(12)
	v_lshlrev_b32_e32 v170, 16, v122
	v_and_b32_e32 v171, 0xffff0000, v122
	v_lshlrev_b32_e32 v172, 16, v123
	v_and_b32_e32 v173, 0xffff0000, v123
	v_lshlrev_b32_e32 v174, 16, v124
	v_and_b32_e32 v175, 0xffff0000, v124
	v_lshlrev_b32_e32 v176, 16, v125
	v_and_b32_e32 v177, 0xffff0000, v125
	s_and_b64 vcc, exec, s[8:9]
	s_cbranch_vccz .Leb_nosig_5
	v_add_f32_e32 v170, v242, v170
	v_add_f32_e32 v171, v243, v171
	v_add_f32_e32 v172, v244, v172
	v_add_f32_e32 v173, v245, v173
	v_add_f32_e32 v174, v246, v174
	v_add_f32_e32 v175, v247, v175
	v_add_f32_e32 v176, v248, v176
	v_add_f32_e32 v177, v249, v177
	v_mul_f32_e32 v170, 0xbfb8aa3b, v170
	v_mul_f32_e32 v171, 0xbfb8aa3b, v171
	v_mul_f32_e32 v172, 0xbfb8aa3b, v172
	v_mul_f32_e32 v173, 0xbfb8aa3b, v173
	v_mul_f32_e32 v174, 0xbfb8aa3b, v174
	v_mul_f32_e32 v175, 0xbfb8aa3b, v175
	v_mul_f32_e32 v176, 0xbfb8aa3b, v176
	v_mul_f32_e32 v177, 0xbfb8aa3b, v177
	v_exp_f32_e32 v170, v170
	v_exp_f32_e32 v171, v171
	v_exp_f32_e32 v172, v172
	v_exp_f32_e32 v173, v173
	v_exp_f32_e32 v174, v174
	v_exp_f32_e32 v175, v175
	v_exp_f32_e32 v176, v176
	v_exp_f32_e32 v177, v177
	s_nop 0
	v_add_f32_e32 v170, 1.0, v170
	v_add_f32_e32 v171, 1.0, v171
	v_add_f32_e32 v172, 1.0, v172
	v_add_f32_e32 v173, 1.0, v173
	v_add_f32_e32 v174, 1.0, v174
	v_add_f32_e32 v175, 1.0, v175
	v_add_f32_e32 v176, 1.0, v176
	v_add_f32_e32 v177, 1.0, v177
	v_rcp_f32_e32 v170, v170
	v_rcp_f32_e32 v171, v171
	v_rcp_f32_e32 v172, v172
	v_rcp_f32_e32 v173, v173
	v_rcp_f32_e32 v174, v174
	v_rcp_f32_e32 v175, v175
	v_rcp_f32_e32 v176, v176
	v_rcp_f32_e32 v177, v177
	s_nop 0
.Leb_nosig_5:
	v_pk_mul_f32 v[86:87], v[86:87], v[170:171]
	v_pk_mul_f32 v[88:89], v[88:89], v[172:173]
	v_pk_mul_f32 v[82:83], v[82:83], v[174:175]
	v_pk_mul_f32 v[84:85], v[84:85], v[176:177]
	s_cmp_lt_i32 s12, 1
	s_cbranch_scc1 .Leb_noadd_5
	v_lshlrev_b32_e32 v170, 16, v126
	v_and_b32_e32 v171, 0xffff0000, v126
	v_lshlrev_b32_e32 v172, 16, v127
	v_and_b32_e32 v173, 0xffff0000, v127
	v_lshlrev_b32_e32 v174, 16, v128
	v_and_b32_e32 v175, 0xffff0000, v128
	v_lshlrev_b32_e32 v176, 16, v129
	v_and_b32_e32 v177, 0xffff0000, v129
	v_pk_add_f32 v[86:87], v[86:87], v[170:171]
	v_pk_add_f32 v[88:89], v[88:89], v[172:173]
	v_pk_add_f32 v[82:83], v[82:83], v[174:175]
	v_pk_add_f32 v[84:85], v[84:85], v[176:177]
.Leb_noadd_5:
	s_nop 1
	v_cvt_pk_bf16_f32 v86, v86, v87
	v_cvt_pk_bf16_f32 v87, v88, v89
	v_cvt_pk_bf16_f32 v88, v82, v83
	v_cvt_pk_bf16_f32 v89, v84, v85
	s_mov_b32 s10, 0x10000
	v_lshl_add_u64 v[250:251], s[10:11], 0, v[166:167]
	global_store_dwordx4 v[250:251], v[86:89], off offset:256
	s_mul_i32 s10, s40, 288
	v_lshl_add_u64 v[250:251], s[10:11], 0, v[148:149]
	global_load_dwordx4 v[82:85], v[250:251], off
	s_mov_b32 s10, 0x48000
	v_lshl_add_u64 v[250:251], s[10:11], 0, v[166:167]
	global_load_dwordx4 v[86:89], v[250:251], off
	s_waitcnt vmcnt(12)
	v_lshlrev_b32_e32 v170, 16, v114
	v_and_b32_e32 v171, 0xffff0000, v114
	v_lshlrev_b32_e32 v172, 16, v115
	v_and_b32_e32 v173, 0xffff0000, v115
	v_lshlrev_b32_e32 v174, 16, v116
	v_and_b32_e32 v175, 0xffff0000, v116
	v_lshlrev_b32_e32 v176, 16, v117
	v_and_b32_e32 v177, 0xffff0000, v117
	s_and_b64 vcc, exec, s[8:9]
	s_cbranch_vccz .Leb_nosig_6
	v_add_f32_e32 v170, v234, v170
	v_add_f32_e32 v171, v235, v171
	v_add_f32_e32 v172, v236, v172
	v_add_f32_e32 v173, v237, v173
	v_add_f32_e32 v174, v238, v174
	v_add_f32_e32 v175, v239, v175
	v_add_f32_e32 v176, v240, v176
	v_add_f32_e32 v177, v241, v177
	v_mul_f32_e32 v170, 0xbfb8aa3b, v170
	v_mul_f32_e32 v171, 0xbfb8aa3b, v171
	v_mul_f32_e32 v172, 0xbfb8aa3b, v172
	v_mul_f32_e32 v173, 0xbfb8aa3b, v173
	v_mul_f32_e32 v174, 0xbfb8aa3b, v174
	v_mul_f32_e32 v175, 0xbfb8aa3b, v175
	v_mul_f32_e32 v176, 0xbfb8aa3b, v176
	v_mul_f32_e32 v177, 0xbfb8aa3b, v177
	v_exp_f32_e32 v170, v170
	v_exp_f32_e32 v171, v171
	v_exp_f32_e32 v172, v172
	v_exp_f32_e32 v173, v173
	v_exp_f32_e32 v174, v174
	v_exp_f32_e32 v175, v175
	v_exp_f32_e32 v176, v176
	v_exp_f32_e32 v177, v177
	s_nop 0
	v_add_f32_e32 v170, 1.0, v170
	v_add_f32_e32 v171, 1.0, v171
	v_add_f32_e32 v172, 1.0, v172
	v_add_f32_e32 v173, 1.0, v173
	v_add_f32_e32 v174, 1.0, v174
	v_add_f32_e32 v175, 1.0, v175
	v_add_f32_e32 v176, 1.0, v176
	v_add_f32_e32 v177, 1.0, v177
	v_rcp_f32_e32 v170, v170
	v_rcp_f32_e32 v171, v171
	v_rcp_f32_e32 v172, v172
	v_rcp_f32_e32 v173, v173
	v_rcp_f32_e32 v174, v174
	v_rcp_f32_e32 v175, v175
	v_rcp_f32_e32 v176, v176
	v_rcp_f32_e32 v177, v177
	s_nop 0
.Leb_nosig_6:
	v_pk_mul_f32 v[78:79], v[78:79], v[170:171]
	v_pk_mul_f32 v[80:81], v[80:81], v[172:173]
	v_pk_mul_f32 v[74:75], v[74:75], v[174:175]
	v_pk_mul_f32 v[76:77], v[76:77], v[176:177]
	s_cmp_lt_i32 s12, 1
	s_cbranch_scc1 .Leb_noadd_6
	v_lshlrev_b32_e32 v170, 16, v118
	v_and_b32_e32 v171, 0xffff0000, v118
	v_lshlrev_b32_e32 v172, 16, v119
	v_and_b32_e32 v173, 0xffff0000, v119
	v_lshlrev_b32_e32 v174, 16, v120
	v_and_b32_e32 v175, 0xffff0000, v120
	v_lshlrev_b32_e32 v176, 16, v121
	v_and_b32_e32 v177, 0xffff0000, v121
	v_pk_add_f32 v[78:79], v[78:79], v[170:171]
	v_pk_add_f32 v[80:81], v[80:81], v[172:173]
	v_pk_add_f32 v[74:75], v[74:75], v[174:175]
	v_pk_add_f32 v[76:77], v[76:77], v[176:177]
; __device__ __forceinline__ unsigned pk2hw(float lo, float hi) { unsigned r; asm("s_nop 1\n\tv_cvt_pk_bf16_f32 %0, %1, %2" : "=v"(r) : "v"(lo), "v"(hi)); return r; }
; __device__ __forceinline__ float sigmoidf_(float x) { return __builtin_amdgcn_rcpf(1.f + __expf(-x)); }
;     __device__ __forceinline__ void operator()(const f32x4 (&acc)[2][2][4][2], const Unit& u, int wr, int wc, int fr, int fq) const {
;     ...
;             for (int m = 0; m < 4; ++m) { const int row = row0 + ai * 128 + m * 16;
; #pragma unroll
;                 for (int bj = 0; bj < 2; ++bj) { const int col = col0 + bj * 128;
;                     const u32x4 gw = *(const u32x4*)(gsrc + (size_t)row * gld + n * D + col);
;                     f32x4 g0 = (f32x4){bflo(gw.x), bfhi(gw.x), bflo(gw.y), bfhi(gw.y)}, g1 = (f32x4){bflo(gw.z), bfhi(gw.z), bflo(gw.w), bfhi(gw.w)};
;                     if (bgate) { const f32x4 b0 = *(const f32x4*)(bgate + n * D + col), b1 = *(const f32x4*)(bgate + n * D + col + 4);
;                         g0[0] = sigmoidf_(g0[0] + b0[0]); g0[1] = sigmoidf_(g0[1] + b0[1]); g0[2] = sigmoidf_(g0[2] + b0[2]); g0[3] = sigmoidf_(g0[3] + b0[3]);
;                         g1[0] = sigmoidf_(g1[0] + b1[0]); g1[1] = sigmoidf_(g1[1] + b1[1]); g1[2] = sigmoidf_(g1[2] + b1[2]); g1[3] = sigmoidf_(g1[3] + b1[3]); }
;                     const f32x4 v0r = acc[ai][bj][m][0] * g0, v1r = acc[ai][bj][m][1] * g1; f32x4 v0 = v0r, v1 = v1r;
;                     bf16_t* mp = merged + (size_t)row * D + col;
;                     if (n > 0) { const u32x4 o = *(const u32x4*)mp; v0[0] += bflo(o.x); v0[1] += bfhi(o.x); v0[2] += bflo(o.y); v0[3] += bfhi(o.y); v1[0] += bflo(o.z); v1[1] += bfhi(o.z); v1[2] += bflo(o.w); v1[3] += bfhi(o.w); }
;                     u32x4 w; w.x = pk2hw(v0[0], v0[1]); w.y = pk2hw(v0[2], v0[3]); w.z = pk2hw(v1[0], v1[1]); w.w = pk2hw(v1[2], v1[3]); *(u32x4*)mp = w; } }
.Leb_noadd_6:
	s_nop 1
	v_cvt_pk_bf16_f32 v78, v78, v79
	v_cvt_pk_bf16_f32 v79, v80, v81
	v_cvt_pk_bf16_f32 v80, v74, v75
	v_cvt_pk_bf16_f32 v81, v76, v77
	s_mov_b32 s10, 0x18000
	v_lshl_add_u64 v[250:251], s[10:11], 0, v[166:167]
	global_store_dwordx4 v[250:251], v[78:81], off
	s_mul_i32 s10, s40, 288
	v_lshl_add_u64 v[250:251], s[10:11], 0, v[148:149]
	global_load_dwordx4 v[74:77], v[250:251], off offset:256
	s_mov_b32 s10, 0x48000
	v_lshl_add_u64 v[250:251], s[10:11], 0, v[166:167]
	global_load_dwordx4 v[78:81], v[250:251], off offset:256
	s_waitcnt vmcnt(12)
	v_lshlrev_b32_e32 v170, 16, v106
	v_and_b32_e32 v171, 0xffff0000, v106
	v_lshlrev_b32_e32 v172, 16, v107
	v_and_b32_e32 v173, 0xffff0000, v107
	v_lshlrev_b32_e32 v174, 16, v108
	v_and_b32_e32 v175, 0xffff0000, v108
	v_lshlrev_b32_e32 v176, 16, v109
	v_and_b32_e32 v177, 0xffff0000, v109
	s_and_b64 vcc, exec, s[8:9]
	s_cbranch_vccz .Leb_nosig_7
	v_add_f32_e32 v170, v242, v170
	v_add_f32_e32 v171, v243, v171
	v_add_f32_e32 v172, v244, v172
	v_add_f32_e32 v173, v245, v173
	v_add_f32_e32 v174, v246, v174
	v_add_f32_e32 v175, v247, v175
	v_add_f32_e32 v176, v248, v176
	v_add_f32_e32 v177, v249, v177
	v_mul_f32_e32 v170, 0xbfb8aa3b, v170
	v_mul_f32_e32 v171, 0xbfb8aa3b, v171
	v_mul_f32_e32 v172, 0xbfb8aa3b, v172
	v_mul_f32_e32 v173, 0xbfb8aa3b, v173
	v_mul_f32_e32 v174, 0xbfb8aa3b, v174
	v_mul_f32_e32 v175, 0xbfb8aa3b, v175
	v_mul_f32_e32 v176, 0xbfb8aa3b, v176
	v_mul_f32_e32 v177, 0xbfb8aa3b, v177
	v_exp_f32_e32 v170, v170
	v_exp_f32_e32 v171, v171
	v_exp_f32_e32 v172, v172
	v_exp_f32_e32 v173, v173
	v_exp_f32_e32 v174, v174
	v_exp_f32_e32 v175, v175
	v_exp_f32_e32 v176, v176
	v_exp_f32_e32 v177, v177
	s_nop 0
	v_add_f32_e32 v170, 1.0, v170
	v_add_f32_e32 v171, 1.0, v171
	v_add_f32_e32 v172, 1.0, v172
	v_add_f32_e32 v173, 1.0, v173
	v_add_f32_e32 v174, 1.0, v174
	v_add_f32_e32 v175, 1.0, v175
	v_add_f32_e32 v176, 1.0, v176
	v_add_f32_e32 v177, 1.0, v177
	v_rcp_f32_e32 v170, v170
	v_rcp_f32_e32 v171, v171
	v_rcp_f32_e32 v172, v172
	v_rcp_f32_e32 v173, v173
	v_rcp_f32_e32 v174, v174
	v_rcp_f32_e32 v175, v175
	v_rcp_f32_e32 v176, v176
	v_rcp_f32_e32 v177, v177
	s_nop 0
.Leb_nosig_7:
	v_pk_mul_f32 v[70:71], v[70:71], v[170:171]
	v_pk_mul_f32 v[72:73], v[72:73], v[172:173]
	v_pk_mul_f32 v[66:67], v[66:67], v[174:175]
	v_pk_mul_f32 v[68:69], v[68:69], v[176:177]
	s_cmp_lt_i32 s12, 1
	s_cbranch_scc1 .Leb_noadd_7
	v_lshlrev_b32_e32 v170, 16, v110
	v_and_b32_e32 v171, 0xffff0000, v110
	v_lshlrev_b32_e32 v172, 16, v111
	v_and_b32_e32 v173, 0xffff0000, v111
	v_lshlrev_b32_e32 v174, 16, v112
	v_and_b32_e32 v175, 0xffff0000, v112
	v_lshlrev_b32_e32 v176, 16, v113
	v_and_b32_e32 v177, 0xffff0000, v113
	v_pk_add_f32 v[70:71], v[70:71], v[170:171]
	v_pk_add_f32 v[72:73], v[72:73], v[172:173]
	v_pk_add_f32 v[66:67], v[66:67], v[174:175]
	v_pk_add_f32 v[68:69], v[68:69], v[176:177]
.Leb_noadd_7:
	s_nop 1
	v_cvt_pk_bf16_f32 v70, v70, v71
	v_cvt_pk_bf16_f32 v71, v72, v73
	v_cvt_pk_bf16_f32 v72, v66, v67
	v_cvt_pk_bf16_f32 v73, v68, v69
	s_mov_b32 s10, 0x18000
	v_lshl_add_u64 v[250:251], s[10:11], 0, v[166:167]
	global_store_dwordx4 v[250:251], v[70:73], off offset:256
	s_mul_i32 s10, s40, 320
	v_lshl_add_u64 v[250:251], s[10:11], 0, v[148:149]
	global_load_dwordx4 v[66:69], v[250:251], off
	s_mov_b32 s10, 0x50000
	v_lshl_add_u64 v[250:251], s[10:11], 0, v[166:167]
	global_load_dwordx4 v[70:73], v[250:251], off
	s_waitcnt vmcnt(12)
	v_lshlrev_b32_e32 v170, 16, v98
	v_and_b32_e32 v171, 0xffff0000, v98
	v_lshlrev_b32_e32 v172, 16, v99
	v_and_b32_e32 v173, 0xffff0000, v99
	v_lshlrev_b32_e32 v174, 16, v100
	v_and_b32_e32 v175, 0xffff0000, v100
	v_lshlrev_b32_e32 v176, 16, v101
	v_and_b32_e32 v177, 0xffff0000, v101
	s_and_b64 vcc, exec, s[8:9]
	s_cbranch_vccz .Leb_nosig_8
	v_add_f32_e32 v170, v234, v170
	v_add_f32_e32 v171, v235, v171
	v_add_f32_e32 v172, v236, v172
	v_add_f32_e32 v173, v237, v173
	v_add_f32_e32 v174, v238, v174
	v_add_f32_e32 v175, v239, v175
	v_add_f32_e32 v176, v240, v176
	v_add_f32_e32 v177, v241, v177
	v_mul_f32_e32 v170, 0xbfb8aa3b, v170
	v_mul_f32_e32 v171, 0xbfb8aa3b, v171
	v_mul_f32_e32 v172, 0xbfb8aa3b, v172
	v_mul_f32_e32 v173, 0xbfb8aa3b, v173
	v_mul_f32_e32 v174, 0xbfb8aa3b, v174
	v_mul_f32_e32 v175, 0xbfb8aa3b, v175
	v_mul_f32_e32 v176, 0xbfb8aa3b, v176
	v_mul_f32_e32 v177, 0xbfb8aa3b, v177
	v_exp_f32_e32 v170, v170
	v_exp_f32_e32 v171, v171
	v_exp_f32_e32 v172, v172
	v_exp_f32_e32 v173, v173
	v_exp_f32_e32 v174, v174
	v_exp_f32_e32 v175, v175
	v_exp_f32_e32 v176, v176
	v_exp_f32_e32 v177, v177
	s_nop 0
	v_add_f32_e32 v170, 1.0, v170
	v_add_f32_e32 v171, 1.0, v171
	v_add_f32_e32 v172, 1.0, v172
	v_add_f32_e32 v173, 1.0, v173
	v_add_f32_e32 v174, 1.0, v174
	v_add_f32_e32 v175, 1.0, v175
	v_add_f32_e32 v176, 1.0, v176
	v_add_f32_e32 v177, 1.0, v177
	v_rcp_f32_e32 v170, v170
	v_rcp_f32_e32 v171, v171
	v_rcp_f32_e32 v172, v172
	v_rcp_f32_e32 v173, v173
	v_rcp_f32_e32 v174, v174
	v_rcp_f32_e32 v175, v175
	v_rcp_f32_e32 v176, v176
	v_rcp_f32_e32 v177, v177
	s_nop 0
.Leb_nosig_8:
	v_pk_mul_f32 v[62:63], v[62:63], v[170:171]
	v_pk_mul_f32 v[64:65], v[64:65], v[172:173]
	v_pk_mul_f32 v[58:59], v[58:59], v[174:175]
	v_pk_mul_f32 v[60:61], v[60:61], v[176:177]
	s_cmp_lt_i32 s12, 1
	s_cbranch_scc1 .Leb_noadd_8
	v_lshlrev_b32_e32 v170, 16, v102
	v_and_b32_e32 v171, 0xffff0000, v102
	v_lshlrev_b32_e32 v172, 16, v103
	v_and_b32_e32 v173, 0xffff0000, v103
	v_lshlrev_b32_e32 v174, 16, v104
	v_and_b32_e32 v175, 0xffff0000, v104
	v_lshlrev_b32_e32 v176, 16, v105
	v_and_b32_e32 v177, 0xffff0000, v105
	v_pk_add_f32 v[62:63], v[62:63], v[170:171]
	v_pk_add_f32 v[64:65], v[64:65], v[172:173]
	v_pk_add_f32 v[58:59], v[58:59], v[174:175]
	v_pk_add_f32 v[60:61], v[60:61], v[176:177]
; __device__ __forceinline__ unsigned pk2hw(float lo, float hi) { unsigned r; asm("s_nop 1\n\tv_cvt_pk_bf16_f32 %0, %1, %2" : "=v"(r) : "v"(lo), "v"(hi)); return r; }
; __device__ __forceinline__ float sigmoidf_(float x) { return __builtin_amdgcn_rcpf(1.f + __expf(-x)); }
;     __device__ __forceinline__ void operator()(const f32x4 (&acc)[2][2][4][2], const Unit& u, int wr, int wc, int fr, int fq) const {
;     ...
;             for (int m = 0; m < 4; ++m) { const int row = row0 + ai * 128 + m * 16;
; #pragma unroll
;                 for (int bj = 0; bj < 2; ++bj) { const int col = col0 + bj * 128;
;                     const u32x4 gw = *(const u32x4*)(gsrc + (size_t)row * gld + n * D + col);
;                     f32x4 g0 = (f32x4){bflo(gw.x), bfhi(gw.x), bflo(gw.y), bfhi(gw.y)}, g1 = (f32x4){bflo(gw.z), bfhi(gw.z), bflo(gw.w), bfhi(gw.w)};
;                     if (bgate) { const f32x4 b0 = *(const f32x4*)(bgate + n * D + col), b1 = *(const f32x4*)(bgate + n * D + col + 4);
;                         g0[0] = sigmoidf_(g0[0] + b0[0]); g0[1] = sigmoidf_(g0[1] + b0[1]); g0[2] = sigmoidf_(g0[2] + b0[2]); g0[3] = sigmoidf_(g0[3] + b0[3]);
;                         g1[0] = sigmoidf_(g1[0] + b1[0]); g1[1] = sigmoidf_(g1[1] + b1[1]); g1[2] = sigmoidf_(g1[2] + b1[2]); g1[3] = sigmoidf_(g1[3] + b1[3]); }
;                     const f32x4 v0r = acc[ai][bj][m][0] * g0, v1r = acc[ai][bj][m][1] * g1; f32x4 v0 = v0r, v1 = v1r;
;                     bf16_t* mp = merged + (size_t)row * D + col;
;                     if (n > 0) { const u32x4 o = *(const u32x4*)mp; v0[0] += bflo(o.x); v0[1] += bfhi(o.x); v0[2] += bflo(o.y); v0[3] += bfhi(o.y); v1[0] += bflo(o.z); v1[1] += bfhi(o.z); v1[2] += bflo(o.w); v1[3] += bfhi(o.w); }
;                     u32x4 w; w.x = pk2hw(v0[0], v0[1]); w.y = pk2hw(v0[2], v0[3]); w.z = pk2hw(v1[0], v1[1]); w.w = pk2hw(v1[2], v1[3]); *(u32x4*)mp = w; } }
.Leb_noadd_8:
	s_nop 1
	v_cvt_pk_bf16_f32 v62, v62, v63
	v_cvt_pk_bf16_f32 v63, v64, v65
	v_cvt_pk_bf16_f32 v64, v58, v59
	v_cvt_pk_bf16_f32 v65, v60, v61
	s_mov_b32 s10, 0x40000
	v_lshl_add_u64 v[250:251], s[10:11], 0, v[166:167]
	global_store_dwordx4 v[250:251], v[62:65], off
	s_mul_i32 s10, s40, 320
	v_lshl_add_u64 v[250:251], s[10:11], 0, v[148:149]
	global_load_dwordx4 v[58:61], v[250:251], off offset:256
	s_mov_b32 s10, 0x50000
	v_lshl_add_u64 v[250:251], s[10:11], 0, v[166:167]
	global_load_dwordx4 v[62:65], v[250:251], off offset:256
	s_waitcnt vmcnt(12)
	v_lshlrev_b32_e32 v170, 16, v90
	v_and_b32_e32 v171, 0xffff0000, v90
	v_lshlrev_b32_e32 v172, 16, v91
	v_and_b32_e32 v173, 0xffff0000, v91
	v_lshlrev_b32_e32 v174, 16, v92
	v_and_b32_e32 v175, 0xffff0000, v92
	v_lshlrev_b32_e32 v176, 16, v93
	v_and_b32_e32 v177, 0xffff0000, v93
	s_and_b64 vcc, exec, s[8:9]
	s_cbranch_vccz .Leb_nosig_9
	v_add_f32_e32 v170, v242, v170
	v_add_f32_e32 v171, v243, v171
	v_add_f32_e32 v172, v244, v172
	v_add_f32_e32 v173, v245, v173
	v_add_f32_e32 v174, v246, v174
	v_add_f32_e32 v175, v247, v175
	v_add_f32_e32 v176, v248, v176
	v_add_f32_e32 v177, v249, v177
	v_mul_f32_e32 v170, 0xbfb8aa3b, v170
	v_mul_f32_e32 v171, 0xbfb8aa3b, v171
	v_mul_f32_e32 v172, 0xbfb8aa3b, v172
	v_mul_f32_e32 v173, 0xbfb8aa3b, v173
	v_mul_f32_e32 v174, 0xbfb8aa3b, v174
	v_mul_f32_e32 v175, 0xbfb8aa3b, v175
	v_mul_f32_e32 v176, 0xbfb8aa3b, v176
	v_mul_f32_e32 v177, 0xbfb8aa3b, v177
	v_exp_f32_e32 v170, v170
	v_exp_f32_e32 v171, v171
	v_exp_f32_e32 v172, v172
	v_exp_f32_e32 v173, v173
	v_exp_f32_e32 v174, v174
	v_exp_f32_e32 v175, v175
	v_exp_f32_e32 v176, v176
	v_exp_f32_e32 v177, v177
	s_nop 0
	v_add_f32_e32 v170, 1.0, v170
	v_add_f32_e32 v171, 1.0, v171
	v_add_f32_e32 v172, 1.0, v172
	v_add_f32_e32 v173, 1.0, v173
	v_add_f32_e32 v174, 1.0, v174
	v_add_f32_e32 v175, 1.0, v175
	v_add_f32_e32 v176, 1.0, v176
	v_add_f32_e32 v177, 1.0, v177
	v_rcp_f32_e32 v170, v170
	v_rcp_f32_e32 v171, v171
	v_rcp_f32_e32 v172, v172
	v_rcp_f32_e32 v173, v173
	v_rcp_f32_e32 v174, v174
	v_rcp_f32_e32 v175, v175
	v_rcp_f32_e32 v176, v176
	v_rcp_f32_e32 v177, v177
	s_nop 0
.Leb_nosig_9:
	v_pk_mul_f32 v[54:55], v[54:55], v[170:171]
	v_pk_mul_f32 v[56:57], v[56:57], v[172:173]
	v_pk_mul_f32 v[50:51], v[50:51], v[174:175]
	v_pk_mul_f32 v[52:53], v[52:53], v[176:177]
	s_cmp_lt_i32 s12, 1
	s_cbranch_scc1 .Leb_noadd_9
	v_lshlrev_b32_e32 v170, 16, v94
	v_and_b32_e32 v171, 0xffff0000, v94
	v_lshlrev_b32_e32 v172, 16, v95
	v_and_b32_e32 v173, 0xffff0000, v95
	v_lshlrev_b32_e32 v174, 16, v96
	v_and_b32_e32 v175, 0xffff0000, v96
	v_lshlrev_b32_e32 v176, 16, v97
	v_and_b32_e32 v177, 0xffff0000, v97
	v_pk_add_f32 v[54:55], v[54:55], v[170:171]
	v_pk_add_f32 v[56:57], v[56:57], v[172:173]
	v_pk_add_f32 v[50:51], v[50:51], v[174:175]
	v_pk_add_f32 v[52:53], v[52:53], v[176:177]
.Leb_noadd_9:
	s_nop 1
	v_cvt_pk_bf16_f32 v54, v54, v55
	v_cvt_pk_bf16_f32 v55, v56, v57
	v_cvt_pk_bf16_f32 v56, v50, v51
	v_cvt_pk_bf16_f32 v57, v52, v53
	s_mov_b32 s10, 0x40000
	v_lshl_add_u64 v[250:251], s[10:11], 0, v[166:167]
	global_store_dwordx4 v[250:251], v[54:57], off offset:256
	s_mul_i32 s10, s40, 352
	v_lshl_add_u64 v[250:251], s[10:11], 0, v[148:149]
	global_load_dwordx4 v[50:53], v[250:251], off
	s_mov_b32 s10, 0x58000
	v_lshl_add_u64 v[250:251], s[10:11], 0, v[166:167]
	global_load_dwordx4 v[54:57], v[250:251], off
	s_waitcnt vmcnt(12)
	v_lshlrev_b32_e32 v170, 16, v82
	v_and_b32_e32 v171, 0xffff0000, v82
	v_lshlrev_b32_e32 v172, 16, v83
	v_and_b32_e32 v173, 0xffff0000, v83
	v_lshlrev_b32_e32 v174, 16, v84
	v_and_b32_e32 v175, 0xffff0000, v84
	v_lshlrev_b32_e32 v176, 16, v85
	v_and_b32_e32 v177, 0xffff0000, v85
	s_and_b64 vcc, exec, s[8:9]
	s_cbranch_vccz .Leb_nosig_10
	v_add_f32_e32 v170, v234, v170
	v_add_f32_e32 v171, v235, v171
	v_add_f32_e32 v172, v236, v172
	v_add_f32_e32 v173, v237, v173
	v_add_f32_e32 v174, v238, v174
	v_add_f32_e32 v175, v239, v175
	v_add_f32_e32 v176, v240, v176
	v_add_f32_e32 v177, v241, v177
	v_mul_f32_e32 v170, 0xbfb8aa3b, v170
	v_mul_f32_e32 v171, 0xbfb8aa3b, v171
	v_mul_f32_e32 v172, 0xbfb8aa3b, v172
	v_mul_f32_e32 v173, 0xbfb8aa3b, v173
	v_mul_f32_e32 v174, 0xbfb8aa3b, v174
	v_mul_f32_e32 v175, 0xbfb8aa3b, v175
	v_mul_f32_e32 v176, 0xbfb8aa3b, v176
	v_mul_f32_e32 v177, 0xbfb8aa3b, v177
	v_exp_f32_e32 v170, v170
	v_exp_f32_e32 v171, v171
	v_exp_f32_e32 v172, v172
	v_exp_f32_e32 v173, v173
	v_exp_f32_e32 v174, v174
	v_exp_f32_e32 v175, v175
	v_exp_f32_e32 v176, v176
	v_exp_f32_e32 v177, v177
	s_nop 0
	v_add_f32_e32 v170, 1.0, v170
	v_add_f32_e32 v171, 1.0, v171
	v_add_f32_e32 v172, 1.0, v172
	v_add_f32_e32 v173, 1.0, v173
	v_add_f32_e32 v174, 1.0, v174
	v_add_f32_e32 v175, 1.0, v175
	v_add_f32_e32 v176, 1.0, v176
	v_add_f32_e32 v177, 1.0, v177
	v_rcp_f32_e32 v170, v170
	v_rcp_f32_e32 v171, v171
	v_rcp_f32_e32 v172, v172
	v_rcp_f32_e32 v173, v173
	v_rcp_f32_e32 v174, v174
	v_rcp_f32_e32 v175, v175
	v_rcp_f32_e32 v176, v176
	v_rcp_f32_e32 v177, v177
	s_nop 0
.Leb_nosig_10:
	v_pk_mul_f32 v[46:47], v[46:47], v[170:171]
	v_pk_mul_f32 v[48:49], v[48:49], v[172:173]
	v_pk_mul_f32 v[42:43], v[42:43], v[174:175]
	v_pk_mul_f32 v[44:45], v[44:45], v[176:177]
	s_cmp_lt_i32 s12, 1
	s_cbranch_scc1 .Leb_noadd_10
	v_lshlrev_b32_e32 v170, 16, v86
	v_and_b32_e32 v171, 0xffff0000, v86
	v_lshlrev_b32_e32 v172, 16, v87
	v_and_b32_e32 v173, 0xffff0000, v87
	v_lshlrev_b32_e32 v174, 16, v88
	v_and_b32_e32 v175, 0xffff0000, v88
	v_lshlrev_b32_e32 v176, 16, v89
	v_and_b32_e32 v177, 0xffff0000, v89
	v_pk_add_f32 v[46:47], v[46:47], v[170:171]
	v_pk_add_f32 v[48:49], v[48:49], v[172:173]
	v_pk_add_f32 v[42:43], v[42:43], v[174:175]
	v_pk_add_f32 v[44:45], v[44:45], v[176:177]
; __device__ __forceinline__ unsigned pk2hw(float lo, float hi) { unsigned r; asm("s_nop 1\n\tv_cvt_pk_bf16_f32 %0, %1, %2" : "=v"(r) : "v"(lo), "v"(hi)); return r; }
; __device__ __forceinline__ float sigmoidf_(float x) { return __builtin_amdgcn_rcpf(1.f + __expf(-x)); }
;     __device__ __forceinline__ void operator()(const f32x4 (&acc)[2][2][4][2], const Unit& u, int wr, int wc, int fr, int fq) const {
;     ...
;             for (int m = 0; m < 4; ++m) { const int row = row0 + ai * 128 + m * 16;
; #pragma unroll
;                 for (int bj = 0; bj < 2; ++bj) { const int col = col0 + bj * 128;
;                     const u32x4 gw = *(const u32x4*)(gsrc + (size_t)row * gld + n * D + col);
;                     f32x4 g0 = (f32x4){bflo(gw.x), bfhi(gw.x), bflo(gw.y), bfhi(gw.y)}, g1 = (f32x4){bflo(gw.z), bfhi(gw.z), bflo(gw.w), bfhi(gw.w)};
;                     if (bgate) { const f32x4 b0 = *(const f32x4*)(bgate + n * D + col), b1 = *(const f32x4*)(bgate + n * D + col + 4);
;                         g0[0] = sigmoidf_(g0[0] + b0[0]); g0[1] = sigmoidf_(g0[1] + b0[1]); g0[2] = sigmoidf_(g0[2] + b0[2]); g0[3] = sigmoidf_(g0[3] + b0[3]);
;                         g1[0] = sigmoidf_(g1[0] + b1[0]); g1[1] = sigmoidf_(g1[1] + b1[1]); g1[2] = sigmoidf_(g1[2] + b1[2]); g1[3] = sigmoidf_(g1[3] + b1[3]); }
;                     const f32x4 v0r = acc[ai][bj][m][0] * g0, v1r = acc[ai][bj][m][1] * g1; f32x4 v0 = v0r, v1 = v1r;
;                     bf16_t* mp = merged + (size_t)row * D + col;
;                     if (n > 0) { const u32x4 o = *(const u32x4*)mp; v0[0] += bflo(o.x); v0[1] += bfhi(o.x); v0[2] += bflo(o.y); v0[3] += bfhi(o.y); v1[0] += bflo(o.z); v1[1] += bfhi(o.z); v1[2] += bflo(o.w); v1[3] += bfhi(o.w); }
;                     u32x4 w; w.x = pk2hw(v0[0], v0[1]); w.y = pk2hw(v0[2], v0[3]); w.z = pk2hw(v1[0], v1[1]); w.w = pk2hw(v1[2], v1[3]); *(u32x4*)mp = w; } }
.Leb_noadd_10:
	s_nop 1
	v_cvt_pk_bf16_f32 v46, v46, v47
	v_cvt_pk_bf16_f32 v47, v48, v49
	v_cvt_pk_bf16_f32 v48, v42, v43
	v_cvt_pk_bf16_f32 v49, v44, v45
	s_mov_b32 s10, 0x48000
	v_lshl_add_u64 v[250:251], s[10:11], 0, v[166:167]
	global_store_dwordx4 v[250:251], v[46:49], off
	s_mul_i32 s10, s40, 352
	v_lshl_add_u64 v[250:251], s[10:11], 0, v[148:149]
	global_load_dwordx4 v[42:45], v[250:251], off offset:256
	s_mov_b32 s10, 0x58000
	v_lshl_add_u64 v[250:251], s[10:11], 0, v[166:167]
	global_load_dwordx4 v[46:49], v[250:251], off offset:256
	s_waitcnt vmcnt(12)
	v_lshlrev_b32_e32 v170, 16, v74
	v_and_b32_e32 v171, 0xffff0000, v74
	v_lshlrev_b32_e32 v172, 16, v75
	v_and_b32_e32 v173, 0xffff0000, v75
	v_lshlrev_b32_e32 v174, 16, v76
	v_and_b32_e32 v175, 0xffff0000, v76
	v_lshlrev_b32_e32 v176, 16, v77
	v_and_b32_e32 v177, 0xffff0000, v77
	s_and_b64 vcc, exec, s[8:9]
	s_cbranch_vccz .Leb_nosig_11
	v_add_f32_e32 v170, v242, v170
	v_add_f32_e32 v171, v243, v171
	v_add_f32_e32 v172, v244, v172
	v_add_f32_e32 v173, v245, v173
	v_add_f32_e32 v174, v246, v174
	v_add_f32_e32 v175, v247, v175
	v_add_f32_e32 v176, v248, v176
	v_add_f32_e32 v177, v249, v177
	v_mul_f32_e32 v170, 0xbfb8aa3b, v170
	v_mul_f32_e32 v171, 0xbfb8aa3b, v171
	v_mul_f32_e32 v172, 0xbfb8aa3b, v172
	v_mul_f32_e32 v173, 0xbfb8aa3b, v173
	v_mul_f32_e32 v174, 0xbfb8aa3b, v174
	v_mul_f32_e32 v175, 0xbfb8aa3b, v175
	v_mul_f32_e32 v176, 0xbfb8aa3b, v176
	v_mul_f32_e32 v177, 0xbfb8aa3b, v177
	v_exp_f32_e32 v170, v170
	v_exp_f32_e32 v171, v171
	v_exp_f32_e32 v172, v172
	v_exp_f32_e32 v173, v173
	v_exp_f32_e32 v174, v174
	v_exp_f32_e32 v175, v175
	v_exp_f32_e32 v176, v176
	v_exp_f32_e32 v177, v177
	s_nop 0
	v_add_f32_e32 v170, 1.0, v170
	v_add_f32_e32 v171, 1.0, v171
	v_add_f32_e32 v172, 1.0, v172
	v_add_f32_e32 v173, 1.0, v173
	v_add_f32_e32 v174, 1.0, v174
	v_add_f32_e32 v175, 1.0, v175
	v_add_f32_e32 v176, 1.0, v176
	v_add_f32_e32 v177, 1.0, v177
	v_rcp_f32_e32 v170, v170
	v_rcp_f32_e32 v171, v171
	v_rcp_f32_e32 v172, v172
	v_rcp_f32_e32 v173, v173
	v_rcp_f32_e32 v174, v174
	v_rcp_f32_e32 v175, v175
	v_rcp_f32_e32 v176, v176
	v_rcp_f32_e32 v177, v177
	s_nop 0
.Leb_nosig_11:
	v_pk_mul_f32 v[38:39], v[38:39], v[170:171]
	v_pk_mul_f32 v[40:41], v[40:41], v[172:173]
	v_pk_mul_f32 v[34:35], v[34:35], v[174:175]
	v_pk_mul_f32 v[36:37], v[36:37], v[176:177]
	s_cmp_lt_i32 s12, 1
	s_cbranch_scc1 .Leb_noadd_11
	v_lshlrev_b32_e32 v170, 16, v78
	v_and_b32_e32 v171, 0xffff0000, v78
	v_lshlrev_b32_e32 v172, 16, v79
	v_and_b32_e32 v173, 0xffff0000, v79
	v_lshlrev_b32_e32 v174, 16, v80
	v_and_b32_e32 v175, 0xffff0000, v80
	v_lshlrev_b32_e32 v176, 16, v81
	v_and_b32_e32 v177, 0xffff0000, v81
	v_pk_add_f32 v[38:39], v[38:39], v[170:171]
	v_pk_add_f32 v[40:41], v[40:41], v[172:173]
	v_pk_add_f32 v[34:35], v[34:35], v[174:175]
	v_pk_add_f32 v[36:37], v[36:37], v[176:177]
.Leb_noadd_11:
	s_nop 1
	v_cvt_pk_bf16_f32 v38, v38, v39
	v_cvt_pk_bf16_f32 v39, v40, v41
	v_cvt_pk_bf16_f32 v40, v34, v35
	v_cvt_pk_bf16_f32 v41, v36, v37
	s_mov_b32 s10, 0x48000
	v_lshl_add_u64 v[250:251], s[10:11], 0, v[166:167]
	global_store_dwordx4 v[250:251], v[38:41], off offset:256
	s_waitcnt vmcnt(10)
	v_lshlrev_b32_e32 v170, 16, v66
	v_and_b32_e32 v171, 0xffff0000, v66
	v_lshlrev_b32_e32 v172, 16, v67
	v_and_b32_e32 v173, 0xffff0000, v67
	v_lshlrev_b32_e32 v174, 16, v68
	v_and_b32_e32 v175, 0xffff0000, v68
	v_lshlrev_b32_e32 v176, 16, v69
	v_and_b32_e32 v177, 0xffff0000, v69
	s_and_b64 vcc, exec, s[8:9]
	s_cbranch_vccz .Leb_nosig_12
	v_add_f32_e32 v170, v234, v170
	v_add_f32_e32 v171, v235, v171
	v_add_f32_e32 v172, v236, v172
	v_add_f32_e32 v173, v237, v173
	v_add_f32_e32 v174, v238, v174
	v_add_f32_e32 v175, v239, v175
	v_add_f32_e32 v176, v240, v176
	v_add_f32_e32 v177, v241, v177
	v_mul_f32_e32 v170, 0xbfb8aa3b, v170
	v_mul_f32_e32 v171, 0xbfb8aa3b, v171
	v_mul_f32_e32 v172, 0xbfb8aa3b, v172
	v_mul_f32_e32 v173, 0xbfb8aa3b, v173
	v_mul_f32_e32 v174, 0xbfb8aa3b, v174
	v_mul_f32_e32 v175, 0xbfb8aa3b, v175
	v_mul_f32_e32 v176, 0xbfb8aa3b, v176
	v_mul_f32_e32 v177, 0xbfb8aa3b, v177
	v_exp_f32_e32 v170, v170
	v_exp_f32_e32 v171, v171
	v_exp_f32_e32 v172, v172
	v_exp_f32_e32 v173, v173
	v_exp_f32_e32 v174, v174
	v_exp_f32_e32 v175, v175
	v_exp_f32_e32 v176, v176
	v_exp_f32_e32 v177, v177
	s_nop 0
	v_add_f32_e32 v170, 1.0, v170
	v_add_f32_e32 v171, 1.0, v171
	v_add_f32_e32 v172, 1.0, v172
	v_add_f32_e32 v173, 1.0, v173
	v_add_f32_e32 v174, 1.0, v174
	v_add_f32_e32 v175, 1.0, v175
	v_add_f32_e32 v176, 1.0, v176
	v_add_f32_e32 v177, 1.0, v177
	v_rcp_f32_e32 v170, v170
	v_rcp_f32_e32 v171, v171
	v_rcp_f32_e32 v172, v172
	v_rcp_f32_e32 v173, v173
	v_rcp_f32_e32 v174, v174
	v_rcp_f32_e32 v175, v175
	v_rcp_f32_e32 v176, v176
	v_rcp_f32_e32 v177, v177
	s_nop 0
.Leb_nosig_12:
	v_pk_mul_f32 v[30:31], v[30:31], v[170:171]
	v_pk_mul_f32 v[32:33], v[32:33], v[172:173]
	v_pk_mul_f32 v[26:27], v[26:27], v[174:175]
	v_pk_mul_f32 v[28:29], v[28:29], v[176:177]
	s_cmp_lt_i32 s12, 1
	s_cbranch_scc1 .Leb_noadd_12
	v_lshlrev_b32_e32 v170, 16, v70
	v_and_b32_e32 v171, 0xffff0000, v70
	v_lshlrev_b32_e32 v172, 16, v71
	v_and_b32_e32 v173, 0xffff0000, v71
	v_lshlrev_b32_e32 v174, 16, v72
	v_and_b32_e32 v175, 0xffff0000, v72
	v_lshlrev_b32_e32 v176, 16, v73
	v_and_b32_e32 v177, 0xffff0000, v73
	v_pk_add_f32 v[30:31], v[30:31], v[170:171]
	v_pk_add_f32 v[32:33], v[32:33], v[172:173]
	v_pk_add_f32 v[26:27], v[26:27], v[174:175]
	v_pk_add_f32 v[28:29], v[28:29], v[176:177]
; __device__ __forceinline__ unsigned pk2hw(float lo, float hi) { unsigned r; asm("s_nop 1\n\tv_cvt_pk_bf16_f32 %0, %1, %2" : "=v"(r) : "v"(lo), "v"(hi)); return r; }
; __device__ __forceinline__ float sigmoidf_(float x) { return __builtin_amdgcn_rcpf(1.f + __expf(-x)); }
;     __device__ __forceinline__ void operator()(const f32x4 (&acc)[2][2][4][2], const Unit& u, int wr, int wc, int fr, int fq) const {
;     ...
;             for (int m = 0; m < 4; ++m) { const int row = row0 + ai * 128 + m * 16;
; #pragma unroll
;                 for (int bj = 0; bj < 2; ++bj) { const int col = col0 + bj * 128;
;                     const u32x4 gw = *(const u32x4*)(gsrc + (size_t)row * gld + n * D + col);
;                     f32x4 g0 = (f32x4){bflo(gw.x), bfhi(gw.x), bflo(gw.y), bfhi(gw.y)}, g1 = (f32x4){bflo(gw.z), bfhi(gw.z), bflo(gw.w), bfhi(gw.w)};
;                     if (bgate) { const f32x4 b0 = *(const f32x4*)(bgate + n * D + col), b1 = *(const f32x4*)(bgate + n * D + col + 4);
;                         g0[0] = sigmoidf_(g0[0] + b0[0]); g0[1] = sigmoidf_(g0[1] + b0[1]); g0[2] = sigmoidf_(g0[2] + b0[2]); g0[3] = sigmoidf_(g0[3] + b0[3]);
;                         g1[0] = sigmoidf_(g1[0] + b1[0]); g1[1] = sigmoidf_(g1[1] + b1[1]); g1[2] = sigmoidf_(g1[2] + b1[2]); g1[3] = sigmoidf_(g1[3] + b1[3]); }
;                     const f32x4 v0r = acc[ai][bj][m][0] * g0, v1r = acc[ai][bj][m][1] * g1; f32x4 v0 = v0r, v1 = v1r;
;                     bf16_t* mp = merged + (size_t)row * D + col;
;                     if (n > 0) { const u32x4 o = *(const u32x4*)mp; v0[0] += bflo(o.x); v0[1] += bfhi(o.x); v0[2] += bflo(o.y); v0[3] += bfhi(o.y); v1[0] += bflo(o.z); v1[1] += bfhi(o.z); v1[2] += bflo(o.w); v1[3] += bfhi(o.w); }
;                     u32x4 w; w.x = pk2hw(v0[0], v0[1]); w.y = pk2hw(v0[2], v0[3]); w.z = pk2hw(v1[0], v1[1]); w.w = pk2hw(v1[2], v1[3]); *(u32x4*)mp = w; } }
.Leb_noadd_12:
	s_nop 1
	v_cvt_pk_bf16_f32 v30, v30, v31
	v_cvt_pk_bf16_f32 v31, v32, v33
	v_cvt_pk_bf16_f32 v32, v26, v27
	v_cvt_pk_bf16_f32 v33, v28, v29
	s_mov_b32 s10, 0x50000
	v_lshl_add_u64 v[250:251], s[10:11], 0, v[166:167]
	global_store_dwordx4 v[250:251], v[30:33], off
	s_waitcnt vmcnt(8)
	v_lshlrev_b32_e32 v170, 16, v58
	v_and_b32_e32 v171, 0xffff0000, v58
	v_lshlrev_b32_e32 v172, 16, v59
	v_and_b32_e32 v173, 0xffff0000, v59
	v_lshlrev_b32_e32 v174, 16, v60
	v_and_b32_e32 v175, 0xffff0000, v60
	v_lshlrev_b32_e32 v176, 16, v61
	v_and_b32_e32 v177, 0xffff0000, v61
	s_and_b64 vcc, exec, s[8:9]
	s_cbranch_vccz .Leb_nosig_13
	v_add_f32_e32 v170, v242, v170
	v_add_f32_e32 v171, v243, v171
	v_add_f32_e32 v172, v244, v172
	v_add_f32_e32 v173, v245, v173
	v_add_f32_e32 v174, v246, v174
	v_add_f32_e32 v175, v247, v175
	v_add_f32_e32 v176, v248, v176
	v_add_f32_e32 v177, v249, v177
	v_mul_f32_e32 v170, 0xbfb8aa3b, v170
	v_mul_f32_e32 v171, 0xbfb8aa3b, v171
	v_mul_f32_e32 v172, 0xbfb8aa3b, v172
	v_mul_f32_e32 v173, 0xbfb8aa3b, v173
	v_mul_f32_e32 v174, 0xbfb8aa3b, v174
	v_mul_f32_e32 v175, 0xbfb8aa3b, v175
	v_mul_f32_e32 v176, 0xbfb8aa3b, v176
	v_mul_f32_e32 v177, 0xbfb8aa3b, v177
	v_exp_f32_e32 v170, v170
	v_exp_f32_e32 v171, v171
	v_exp_f32_e32 v172, v172
	v_exp_f32_e32 v173, v173
	v_exp_f32_e32 v174, v174
	v_exp_f32_e32 v175, v175
	v_exp_f32_e32 v176, v176
	v_exp_f32_e32 v177, v177
	s_nop 0
	v_add_f32_e32 v170, 1.0, v170
	v_add_f32_e32 v171, 1.0, v171
	v_add_f32_e32 v172, 1.0, v172
	v_add_f32_e32 v173, 1.0, v173
	v_add_f32_e32 v174, 1.0, v174
	v_add_f32_e32 v175, 1.0, v175
	v_add_f32_e32 v176, 1.0, v176
	v_add_f32_e32 v177, 1.0, v177
	v_rcp_f32_e32 v170, v170
	v_rcp_f32_e32 v171, v171
	v_rcp_f32_e32 v172, v172
	v_rcp_f32_e32 v173, v173
	v_rcp_f32_e32 v174, v174
	v_rcp_f32_e32 v175, v175
	v_rcp_f32_e32 v176, v176
	v_rcp_f32_e32 v177, v177
	s_nop 0
.Leb_nosig_13:
	v_pk_mul_f32 v[22:23], v[22:23], v[170:171]
	v_pk_mul_f32 v[24:25], v[24:25], v[172:173]
	v_pk_mul_f32 v[18:19], v[18:19], v[174:175]
	v_pk_mul_f32 v[20:21], v[20:21], v[176:177]
	s_cmp_lt_i32 s12, 1
	s_cbranch_scc1 .Leb_noadd_13
	v_lshlrev_b32_e32 v170, 16, v62
	v_and_b32_e32 v171, 0xffff0000, v62
	v_lshlrev_b32_e32 v172, 16, v63
	v_and_b32_e32 v173, 0xffff0000, v63
	v_lshlrev_b32_e32 v174, 16, v64
	v_and_b32_e32 v175, 0xffff0000, v64
	v_lshlrev_b32_e32 v176, 16, v65
	v_and_b32_e32 v177, 0xffff0000, v65
	v_pk_add_f32 v[22:23], v[22:23], v[170:171]
	v_pk_add_f32 v[24:25], v[24:25], v[172:173]
	v_pk_add_f32 v[18:19], v[18:19], v[174:175]
	v_pk_add_f32 v[20:21], v[20:21], v[176:177]
.Leb_noadd_13:
	s_nop 1
	v_cvt_pk_bf16_f32 v22, v22, v23
	v_cvt_pk_bf16_f32 v23, v24, v25
	v_cvt_pk_bf16_f32 v24, v18, v19
	v_cvt_pk_bf16_f32 v25, v20, v21
	s_mov_b32 s10, 0x50000
	v_lshl_add_u64 v[250:251], s[10:11], 0, v[166:167]
	global_store_dwordx4 v[250:251], v[22:25], off offset:256
	s_waitcnt vmcnt(6)
	v_lshlrev_b32_e32 v170, 16, v50
	v_and_b32_e32 v171, 0xffff0000, v50
	v_lshlrev_b32_e32 v172, 16, v51
	v_and_b32_e32 v173, 0xffff0000, v51
	v_lshlrev_b32_e32 v174, 16, v52
	v_and_b32_e32 v175, 0xffff0000, v52
	v_lshlrev_b32_e32 v176, 16, v53
	v_and_b32_e32 v177, 0xffff0000, v53
	s_and_b64 vcc, exec, s[8:9]
	s_cbranch_vccz .Leb_nosig_14
	v_add_f32_e32 v170, v234, v170
	v_add_f32_e32 v171, v235, v171
	v_add_f32_e32 v172, v236, v172
	v_add_f32_e32 v173, v237, v173
	v_add_f32_e32 v174, v238, v174
	v_add_f32_e32 v175, v239, v175
	v_add_f32_e32 v176, v240, v176
	v_add_f32_e32 v177, v241, v177
	v_mul_f32_e32 v170, 0xbfb8aa3b, v170
	v_mul_f32_e32 v171, 0xbfb8aa3b, v171
	v_mul_f32_e32 v172, 0xbfb8aa3b, v172
	v_mul_f32_e32 v173, 0xbfb8aa3b, v173
	v_mul_f32_e32 v174, 0xbfb8aa3b, v174
	v_mul_f32_e32 v175, 0xbfb8aa3b, v175
	v_mul_f32_e32 v176, 0xbfb8aa3b, v176
	v_mul_f32_e32 v177, 0xbfb8aa3b, v177
	v_exp_f32_e32 v170, v170
	v_exp_f32_e32 v171, v171
	v_exp_f32_e32 v172, v172
	v_exp_f32_e32 v173, v173
	v_exp_f32_e32 v174, v174
	v_exp_f32_e32 v175, v175
	v_exp_f32_e32 v176, v176
	v_exp_f32_e32 v177, v177
	s_nop 0
	v_add_f32_e32 v170, 1.0, v170
	v_add_f32_e32 v171, 1.0, v171
	v_add_f32_e32 v172, 1.0, v172
	v_add_f32_e32 v173, 1.0, v173
	v_add_f32_e32 v174, 1.0, v174
	v_add_f32_e32 v175, 1.0, v175
	v_add_f32_e32 v176, 1.0, v176
	v_add_f32_e32 v177, 1.0, v177
	v_rcp_f32_e32 v170, v170
	v_rcp_f32_e32 v171, v171
	v_rcp_f32_e32 v172, v172
	v_rcp_f32_e32 v173, v173
	v_rcp_f32_e32 v174, v174
	v_rcp_f32_e32 v175, v175
	v_rcp_f32_e32 v176, v176
	v_rcp_f32_e32 v177, v177
	s_nop 0
; #define PG8_BAR __builtin_amdgcn_s_barrier()
; __device__ __forceinline__ float sigmoidf_(float x) { return __builtin_amdgcn_rcpf(1.f + __expf(-x)); }
; template <class Epi, class Sched, bool ALIGN_EPI = false, bool SP2 = false>
; __device__ __forceinline__ void gemm_phase(PG8_LAS unsigned char* lds, const Gemm g, const Sched& S, const Epi& E) {
;     ...
;         if (!has_next) break;
; #pragma unroll
;         for (int a = 0; a < 2; ++a)
; #pragma unroll
;             for (int b = 0; b < 2; ++b)
; #pragma unroll
;                 for (int m = 0; m < 4; ++m)
; #pragma unroll
;                     for (int n = 0; n < 2; ++n) acc[a][b][m][n] = (f32x4){0.f, 0.f, 0.f, 0.f};
;         cur = nxt; cA = nA; cB = nB; ++ui;
;         if constexpr (ALIGN_EPI) { if (wr == 1) PG8_BAR; }
;     }
;     __device__ __forceinline__ void operator()(const f32x4 (&acc)[2][2][4][2], const Unit& u, int wr, int wc, int fr, int fq) const {
;     ...
;             for (int m = 0; m < 4; ++m) { const int row = row0 + ai * 128 + m * 16;
; #pragma unroll
;                 for (int bj = 0; bj < 2; ++bj) { const int col = col0 + bj * 128;
;                     const u32x4 gw = *(const u32x4*)(gsrc + (size_t)row * gld + n * D + col);
;                     f32x4 g0 = (f32x4){bflo(gw.x), bfhi(gw.x), bflo(gw.y), bfhi(gw.y)}, g1 = (f32x4){bflo(gw.z), bfhi(gw.z), bflo(gw.w), bfhi(gw.w)};
;                     if (bgate) { const f32x4 b0 = *(const f32x4*)(bgate + n * D + col), b1 = *(const f32x4*)(bgate + n * D + col + 4);
;                         g0[0] = sigmoidf_(g0[0] + b0[0]); g0[1] = sigmoidf_(g0[1] + b0[1]); g0[2] = sigmoidf_(g0[2] + b0[2]); g0[3] = sigmoidf_(g0[3] + b0[3]);
;                         g1[0] = sigmoidf_(g1[0] + b1[0]); g1[1] = sigmoidf_(g1[1] + b1[1]); g1[2] = sigmoidf_(g1[2] + b1[2]); g1[3] = sigmoidf_(g1[3] + b1[3]); }
;                     const f32x4 v0r = acc[ai][bj][m][0] * g0, v1r = acc[ai][bj][m][1] * g1; f32x4 v0 = v0r, v1 = v1r;
;                     bf16_t* mp = merged + (size_t)row * D + col;
;                     if (n > 0) { const u32x4 o = *(const u32x4*)mp; v0[0] += bflo(o.x); v0[1] += bfhi(o.x); v0[2] += bflo(o.y); v0[3] += bfhi(o.y); v1[0] += bflo(o.z); v1[1] += bfhi(o.z); v1[2] += bflo(o.w); v1[3] += bfhi(o.w); }
;                     u32x4 w; w.x = pk2hw(v0[0], v0[1]); w.y = pk2hw(v0[2], v0[3]); w.z = pk2hw(v1[0], v1[1]); w.w = pk2hw(v1[2], v1[3]); *(u32x4*)mp = w; } }
.Leb_nosig_14:
	v_pk_mul_f32 v[14:15], v[14:15], v[170:171]
	v_pk_mul_f32 v[16:17], v[16:17], v[172:173]
	v_pk_mul_f32 v[10:11], v[10:11], v[174:175]
	v_pk_mul_f32 v[12:13], v[12:13], v[176:177]
	s_cmp_lt_i32 s12, 1
	s_cbranch_scc1 .Leb_noadd_14
	v_lshlrev_b32_e32 v170, 16, v54
	v_and_b32_e32 v171, 0xffff0000, v54
	v_lshlrev_b32_e32 v172, 16, v55
	v_and_b32_e32 v173, 0xffff0000, v55
	v_lshlrev_b32_e32 v174, 16, v56
	v_and_b32_e32 v175, 0xffff0000, v56
	v_lshlrev_b32_e32 v176, 16, v57
	v_and_b32_e32 v177, 0xffff0000, v57
	v_pk_add_f32 v[14:15], v[14:15], v[170:171]
	v_pk_add_f32 v[16:17], v[16:17], v[172:173]
	v_pk_add_f32 v[10:11], v[10:11], v[174:175]
	v_pk_add_f32 v[12:13], v[12:13], v[176:177]
.Leb_noadd_14:
	s_nop 1
	v_cvt_pk_bf16_f32 v14, v14, v15
	v_cvt_pk_bf16_f32 v15, v16, v17
	v_cvt_pk_bf16_f32 v16, v10, v11
	v_cvt_pk_bf16_f32 v17, v12, v13
	s_mov_b32 s10, 0x58000
	v_lshl_add_u64 v[250:251], s[10:11], 0, v[166:167]
	global_store_dwordx4 v[250:251], v[14:17], off
	s_waitcnt vmcnt(4)
	v_lshlrev_b32_e32 v170, 16, v42
	v_and_b32_e32 v171, 0xffff0000, v42
	v_lshlrev_b32_e32 v172, 16, v43
	v_and_b32_e32 v173, 0xffff0000, v43
	v_lshlrev_b32_e32 v174, 16, v44
	v_and_b32_e32 v175, 0xffff0000, v44
	v_lshlrev_b32_e32 v176, 16, v45
	v_and_b32_e32 v177, 0xffff0000, v45
	s_and_b64 vcc, exec, s[8:9]
	s_cbranch_vccz .Leb_nosig_15
	v_add_f32_e32 v170, v242, v170
	v_add_f32_e32 v171, v243, v171
	v_add_f32_e32 v172, v244, v172
	v_add_f32_e32 v173, v245, v173
	v_add_f32_e32 v174, v246, v174
	v_add_f32_e32 v175, v247, v175
	v_add_f32_e32 v176, v248, v176
	v_add_f32_e32 v177, v249, v177
	v_mul_f32_e32 v170, 0xbfb8aa3b, v170
	v_mul_f32_e32 v171, 0xbfb8aa3b, v171
	v_mul_f32_e32 v172, 0xbfb8aa3b, v172
	v_mul_f32_e32 v173, 0xbfb8aa3b, v173
	v_mul_f32_e32 v174, 0xbfb8aa3b, v174
	v_mul_f32_e32 v175, 0xbfb8aa3b, v175
	v_mul_f32_e32 v176, 0xbfb8aa3b, v176
	v_mul_f32_e32 v177, 0xbfb8aa3b, v177
	v_exp_f32_e32 v170, v170
	v_exp_f32_e32 v171, v171
	v_exp_f32_e32 v172, v172
	v_exp_f32_e32 v173, v173
	v_exp_f32_e32 v174, v174
	v_exp_f32_e32 v175, v175
	v_exp_f32_e32 v176, v176
	v_exp_f32_e32 v177, v177
	s_nop 0
	v_add_f32_e32 v170, 1.0, v170
	v_add_f32_e32 v171, 1.0, v171
	v_add_f32_e32 v172, 1.0, v172
	v_add_f32_e32 v173, 1.0, v173
	v_add_f32_e32 v174, 1.0, v174
	v_add_f32_e32 v175, 1.0, v175
	v_add_f32_e32 v176, 1.0, v176
	v_add_f32_e32 v177, 1.0, v177
	v_rcp_f32_e32 v170, v170
	v_rcp_f32_e32 v171, v171
	v_rcp_f32_e32 v172, v172
	v_rcp_f32_e32 v173, v173
	v_rcp_f32_e32 v174, v174
	v_rcp_f32_e32 v175, v175
	v_rcp_f32_e32 v176, v176
	v_rcp_f32_e32 v177, v177
	s_nop 0
.Leb_nosig_15:
	v_pk_mul_f32 v[6:7], v[6:7], v[170:171]
	v_pk_mul_f32 v[8:9], v[8:9], v[172:173]
	v_pk_mul_f32 v[2:3], v[2:3], v[174:175]
	v_pk_mul_f32 v[4:5], v[4:5], v[176:177]
	s_cmp_lt_i32 s12, 1
	s_cbranch_scc1 .Leb_noadd_15
	v_lshlrev_b32_e32 v170, 16, v46
	v_and_b32_e32 v171, 0xffff0000, v46
	v_lshlrev_b32_e32 v172, 16, v47
	v_and_b32_e32 v173, 0xffff0000, v47
	v_lshlrev_b32_e32 v174, 16, v48
	v_and_b32_e32 v175, 0xffff0000, v48
	v_lshlrev_b32_e32 v176, 16, v49
	v_and_b32_e32 v177, 0xffff0000, v49
	v_pk_add_f32 v[6:7], v[6:7], v[170:171]
	v_pk_add_f32 v[8:9], v[8:9], v[172:173]
	v_pk_add_f32 v[2:3], v[2:3], v[174:175]
	v_pk_add_f32 v[4:5], v[4:5], v[176:177]
.Leb_noadd_15:
	s_nop 1
	v_cvt_pk_bf16_f32 v6, v6, v7
	v_cvt_pk_bf16_f32 v7, v8, v9
	v_cvt_pk_bf16_f32 v8, v2, v3
	v_cvt_pk_bf16_f32 v9, v4, v5
	s_mov_b32 s10, 0x58000
	v_lshl_add_u64 v[250:251], s[10:11], 0, v[166:167]
	global_store_dwordx4 v[250:251], v[6:9], off offset:256
	s_cmp_eq_u32 s0, 2
	s_mov_b64 s[0:1], -1
	s_cbranch_scc1 .LBB0_672
	s_andn2_b64 vcc, exec, s[18:19]
	s_cbranch_vccnz .LBB0_671
	s_barrier
	s_branch .LBB0_671

; __device__ __forceinline__ unsigned pk2hw(float lo, float hi) { unsigned r; asm("s_nop 1\n\tv_cvt_pk_bf16_f32 %0, %1, %2" : "=v"(r) : "v"(lo), "v"(hi)); return r; }
;     __device__ __forceinline__ void operator()(const f32x4 (&acc)[2][2][4][2], const Unit& u, int wr, int wc, int fr, int fq) const {
;         asm volatile("" : "+v"(fr), "+v"(fq));
;         const int row0 = u.pm * 256 + wr * 64 + fr, col0 = u.pn * 256 + wc * 32 + 8 * fq;
; #pragma unroll
;         for (int ai = 0; ai < 2; ++ai)
; #pragma unroll
;             for (int m = 0; m < 4; ++m) { const int row = row0 + ai * 128 + m * 16; float sq = 0.f;
; #pragma unroll
;                 for (int bj = 0; bj < 2; ++bj) { const size_t off = (size_t)row * D + col0 + bj * 128;
;                     const f32x4 x0 = *(const f32x4*)(xin + off) + acc[ai][bj][m][0], x1 = *(const f32x4*)(xin + off + 4) + acc[ai][bj][m][1];
;                     *(f32x4*)(xout + off) = x0; *(f32x4*)(xout + off + 4) = x1;
;                     u32x4 w; w.x = pk2hw(x0[0], x0[1]); w.y = pk2hw(x0[2], x0[3]); w.z = pk2hw(x1[0], x1[1]); w.w = pk2hw(x1[2], x1[3]); *(u32x4*)(xb + off) = w;
;                     sq += ((x0[0] * x0[0] + x0[1] * x0[1]) + (x0[2] * x0[2] + x0[3] * x0[3])) + ((x1[0] * x1[0] + x1[1] * x1[1]) + (x1[2] * x1[2] + x1[3] * x1[3])); }
;                 sq += __shfl_xor(sq, 16); sq += __shfl_xor(sq, 32);
;                 if (fq == 0) ssn[(size_t)row * 16 + u.pn * 4 + wc] = sq; }
;     }
.LBB0_1106:
	s_lshl_b32 s0, s52, 8
	v_mov_b32_e32 v140, v145
	v_mov_b32_e32 v143, v144
	s_add_i32 s0, s0, s40
	s_lshl_b32 s22, s49, 2
	v_add_u32_e32 v142, s0, v140
	s_lshl_b32 s0, s49, 8
	s_or_b32 s0, s0, s41
	v_lshl_add_u32 v140, v143, 3, s0
	v_cmp_eq_u32_e32 vcc, 0, v143
	v_ashrrev_i32_e32 v143, 31, v142
	v_ashrrev_i32_e32 v141, 31, v140
	v_lshlrev_b64 v[166:167], 10, v[142:143]
	v_lshl_add_u64 v[166:167], v[166:167], 0, v[140:141]
	v_lshl_add_u64 v[174:175], v[166:167], 2, s[8:9]
	s_mov_b64 s[26:27], vcc
	s_mov_b32 s25, 0
	s_ashr_i32 s23, s22, 31
	v_lshl_add_u64 v[166:167], v[166:167], 1, s[12:13]
	v_lshlrev_b64 v[248:249], 6, v[142:143]
	v_lshl_add_u64 v[248:249], s[14:15], 0, v[248:249]
	v_lshl_add_u64 v[248:249], s[22:23], 2, v[248:249]
	s_lshl_b32 s62, s39, 2
	v_lshl_add_u64 v[248:249], v[248:249], 0, s[62:63]
	s_movk_i32 s24, 0x2000
	v_lshl_add_u64 v[142:143], s[24:25], 0, v[248:249]
	v_xor_b32_e32 v235, 16, v225
	v_xor_b32_e32 v236, 32, v225
	v_lshlrev_b32_e32 v235, 2, v235
	v_lshlrev_b32_e32 v236, 2, v236
	s_mov_b32 s24, 0x0
	v_lshl_add_u64 v[242:243], s[24:25], 0, v[174:175]
	global_load_dwordx4 v[180:183], v[242:243], off
	global_load_dwordx4 v[184:187], v[242:243], off offset:16
	global_load_dwordx4 v[188:191], v[242:243], off offset:512
	global_load_dwordx4 v[192:195], v[242:243], off offset:528
	s_mov_b32 s24, 0x10000
	v_lshl_add_u64 v[242:243], s[24:25], 0, v[174:175]
	global_load_dwordx4 v[196:199], v[242:243], off
	global_load_dwordx4 v[200:203], v[242:243], off offset:16
	global_load_dwordx4 v[204:207], v[242:243], off offset:512
	global_load_dwordx4 v[208:211], v[242:243], off offset:528
	s_mov_b32 s24, 0x20000
	v_lshl_add_u64 v[242:243], s[24:25], 0, v[174:175]
	global_load_dwordx4 v[212:215], v[242:243], off
	global_load_dwordx4 v[216:219], v[242:243], off offset:16
	s_waitcnt vmcnt(8)
	v_pk_add_f32 v[126:127], v[126:127], v[180:181]
	v_pk_add_f32 v[128:129], v[128:129], v[182:183]
	v_pk_add_f32 v[122:123], v[122:123], v[184:185]
	v_pk_add_f32 v[124:125], v[124:125], v[186:187]
	s_mov_b32 s24, 0x0
	v_lshl_add_u64 v[244:245], s[24:25], 0, v[174:175]
	s_mov_b32 s24, 0x0
	v_lshl_add_u64 v[246:247], s[24:25], 0, v[166:167]
	global_store_dwordx4 v[244:245], v[126:129], off
	global_store_dwordx4 v[244:245], v[122:125], off offset:16
	v_cvt_pk_bf16_f32 v176, v126, v127
	v_cvt_pk_bf16_f32 v177, v128, v129
	v_cvt_pk_bf16_f32 v178, v122, v123
	v_cvt_pk_bf16_f32 v179, v124, v125
	v_mul_f32_e32 v238, v127, v127
	v_mul_f32_e32 v240, v123, v123
	v_fmac_f32_e32 v238, v126, v126
	v_mul_f32_e32 v239, v129, v129
	v_fmac_f32_e32 v240, v122, v122
	v_mul_f32_e32 v241, v125, v125
	v_fmac_f32_e32 v239, v128, v128
	v_fmac_f32_e32 v241, v124, v124
	global_store_dwordx4 v[246:247], v[176:179], off
	v_add_f32_e32 v238, v238, v239
	v_add_f32_e32 v240, v240, v241
	v_add_f32_e32 v237, v238, v240
	global_load_dwordx4 v[126:129], v[242:243], off offset:512
	global_load_dwordx4 v[122:125], v[242:243], off offset:528
	s_waitcnt vmcnt(11)
	v_pk_add_f32 v[118:119], v[118:119], v[188:189]
	v_pk_add_f32 v[120:121], v[120:121], v[190:191]
	v_pk_add_f32 v[114:115], v[114:115], v[192:193]
	v_pk_add_f32 v[116:117], v[116:117], v[194:195]
	global_store_dwordx4 v[244:245], v[118:121], off offset:512
	global_store_dwordx4 v[244:245], v[114:117], off offset:528
	v_cvt_pk_bf16_f32 v220, v118, v119
	v_cvt_pk_bf16_f32 v221, v120, v121
	v_cvt_pk_bf16_f32 v222, v114, v115
	v_cvt_pk_bf16_f32 v223, v116, v117
	v_mul_f32_e32 v238, v119, v119
	v_mul_f32_e32 v240, v115, v115
	v_fmac_f32_e32 v238, v118, v118
	v_mul_f32_e32 v239, v121, v121
	v_fmac_f32_e32 v240, v114, v114
	v_mul_f32_e32 v241, v117, v117
	v_fmac_f32_e32 v239, v120, v120
	v_fmac_f32_e32 v241, v116, v116
	global_store_dwordx4 v[246:247], v[220:223], off offset:256
	v_add_f32_e32 v238, v238, v239
	v_add_f32_e32 v240, v240, v241
	v_add_f32_e32 v238, v238, v240
	v_add_f32_e32 v237, v237, v238
	ds_bpermute_b32 v250, v235, v237
	s_mov_b32 s24, 0x30000
	v_lshl_add_u64 v[242:243], s[24:25], 0, v[174:175]
	global_load_dwordx4 v[118:121], v[242:243], off
	global_load_dwordx4 v[114:117], v[242:243], off offset:16
	s_waitcnt lgkmcnt(0)
	v_add_f32_e32 v237, v237, v250
	ds_bpermute_b32 v250, v236, v237
	s_waitcnt lgkmcnt(0)
	s_and_saveexec_b64 s[0:1], s[26:27]
	v_add_f32_e32 v237, v237, v250
	global_store_dword v[248:249], v237, off
	s_or_b64 exec, exec, s[0:1]
	s_waitcnt vmcnt(14)
	v_pk_add_f32 v[110:111], v[110:111], v[196:197]
	v_pk_add_f32 v[112:113], v[112:113], v[198:199]
	v_pk_add_f32 v[106:107], v[106:107], v[200:201]
	v_pk_add_f32 v[108:109], v[108:109], v[202:203]
	s_mov_b32 s24, 0x10000
	v_lshl_add_u64 v[244:245], s[24:25], 0, v[174:175]
	s_mov_b32 s24, 0x8000
	v_lshl_add_u64 v[246:247], s[24:25], 0, v[166:167]
	global_store_dwordx4 v[244:245], v[110:113], off
	global_store_dwordx4 v[244:245], v[106:109], off offset:16
	v_cvt_pk_bf16_f32 v176, v110, v111
	v_cvt_pk_bf16_f32 v177, v112, v113
	v_cvt_pk_bf16_f32 v178, v106, v107
	v_cvt_pk_bf16_f32 v179, v108, v109
	v_mul_f32_e32 v238, v111, v111
	v_mul_f32_e32 v240, v107, v107
	v_fmac_f32_e32 v238, v110, v110
	v_mul_f32_e32 v239, v113, v113
	v_fmac_f32_e32 v240, v106, v106
	v_mul_f32_e32 v241, v109, v109
	v_fmac_f32_e32 v239, v112, v112
	v_fmac_f32_e32 v241, v108, v108
	global_store_dwordx4 v[246:247], v[176:179], off
	v_add_f32_e32 v238, v238, v239
	v_add_f32_e32 v240, v240, v241
	v_add_f32_e32 v237, v238, v240
	global_load_dwordx4 v[110:113], v[242:243], off offset:512
	global_load_dwordx4 v[106:109], v[242:243], off offset:528
	s_waitcnt vmcnt(17)
; __device__ __forceinline__ unsigned pk2hw(float lo, float hi) { unsigned r; asm("s_nop 1\n\tv_cvt_pk_bf16_f32 %0, %1, %2" : "=v"(r) : "v"(lo), "v"(hi)); return r; }
;     __device__ __forceinline__ void operator()(const f32x4 (&acc)[2][2][4][2], const Unit& u, int wr, int wc, int fr, int fq) const {
;         asm volatile("" : "+v"(fr), "+v"(fq));
;         const int row0 = u.pm * 256 + wr * 64 + fr, col0 = u.pn * 256 + wc * 32 + 8 * fq;
; #pragma unroll
;         for (int ai = 0; ai < 2; ++ai)
; #pragma unroll
;             for (int m = 0; m < 4; ++m) { const int row = row0 + ai * 128 + m * 16; float sq = 0.f;
; #pragma unroll
;                 for (int bj = 0; bj < 2; ++bj) { const size_t off = (size_t)row * D + col0 + bj * 128;
;                     const f32x4 x0 = *(const f32x4*)(xin + off) + acc[ai][bj][m][0], x1 = *(const f32x4*)(xin + off + 4) + acc[ai][bj][m][1];
;                     *(f32x4*)(xout + off) = x0; *(f32x4*)(xout + off + 4) = x1;
;                     u32x4 w; w.x = pk2hw(x0[0], x0[1]); w.y = pk2hw(x0[2], x0[3]); w.z = pk2hw(x1[0], x1[1]); w.w = pk2hw(x1[2], x1[3]); *(u32x4*)(xb + off) = w;
;                     sq += ((x0[0] * x0[0] + x0[1] * x0[1]) + (x0[2] * x0[2] + x0[3] * x0[3])) + ((x1[0] * x1[0] + x1[1] * x1[1]) + (x1[2] * x1[2] + x1[3] * x1[3])); }
;                 sq += __shfl_xor(sq, 16); sq += __shfl_xor(sq, 32);
;                 if (fq == 0) ssn[(size_t)row * 16 + u.pn * 4 + wc] = sq; }
;     }
	v_pk_add_f32 v[102:103], v[102:103], v[204:205]
	v_pk_add_f32 v[104:105], v[104:105], v[206:207]
	v_pk_add_f32 v[98:99], v[98:99], v[208:209]
	v_pk_add_f32 v[100:101], v[100:101], v[210:211]
	global_store_dwordx4 v[244:245], v[102:105], off offset:512
	global_store_dwordx4 v[244:245], v[98:101], off offset:528
	v_cvt_pk_bf16_f32 v220, v102, v103
	v_cvt_pk_bf16_f32 v221, v104, v105
	v_cvt_pk_bf16_f32 v222, v98, v99
	v_cvt_pk_bf16_f32 v223, v100, v101
	v_mul_f32_e32 v238, v103, v103
	v_mul_f32_e32 v240, v99, v99
	v_fmac_f32_e32 v238, v102, v102
	v_mul_f32_e32 v239, v105, v105
	v_fmac_f32_e32 v240, v98, v98
	v_mul_f32_e32 v241, v101, v101
	v_fmac_f32_e32 v239, v104, v104
	v_fmac_f32_e32 v241, v100, v100
	global_store_dwordx4 v[246:247], v[220:223], off offset:256
	v_add_f32_e32 v238, v238, v239
	v_add_f32_e32 v240, v240, v241
	v_add_f32_e32 v238, v238, v240
	v_add_f32_e32 v237, v237, v238
	ds_bpermute_b32 v250, v235, v237
	s_mov_b32 s24, 0x80000
	v_lshl_add_u64 v[242:243], s[24:25], 0, v[174:175]
	global_load_dwordx4 v[102:105], v[242:243], off
	global_load_dwordx4 v[98:101], v[242:243], off offset:16
	s_waitcnt lgkmcnt(0)
	v_add_f32_e32 v237, v237, v250
	ds_bpermute_b32 v250, v236, v237
	s_waitcnt lgkmcnt(0)
	s_and_saveexec_b64 s[0:1], s[26:27]
	v_add_f32_e32 v237, v237, v250
	global_store_dword v[248:249], v237, off offset:1024
	s_or_b64 exec, exec, s[0:1]
	s_waitcnt vmcnt(20)
	v_pk_add_f32 v[94:95], v[94:95], v[212:213]
	v_pk_add_f32 v[96:97], v[96:97], v[214:215]
	v_pk_add_f32 v[90:91], v[90:91], v[216:217]
	v_pk_add_f32 v[92:93], v[92:93], v[218:219]
	s_mov_b32 s24, 0x20000
	v_lshl_add_u64 v[244:245], s[24:25], 0, v[174:175]
	s_mov_b32 s24, 0x10000
	v_lshl_add_u64 v[246:247], s[24:25], 0, v[166:167]
	global_store_dwordx4 v[244:245], v[94:97], off
	global_store_dwordx4 v[244:245], v[90:93], off offset:16
	v_cvt_pk_bf16_f32 v176, v94, v95
	v_cvt_pk_bf16_f32 v177, v96, v97
	v_cvt_pk_bf16_f32 v178, v90, v91
	v_cvt_pk_bf16_f32 v179, v92, v93
	v_mul_f32_e32 v238, v95, v95
	v_mul_f32_e32 v240, v91, v91
	v_fmac_f32_e32 v238, v94, v94
	v_mul_f32_e32 v239, v97, v97
	v_fmac_f32_e32 v240, v90, v90
	v_mul_f32_e32 v241, v93, v93
	v_fmac_f32_e32 v239, v96, v96
	v_fmac_f32_e32 v241, v92, v92
	global_store_dwordx4 v[246:247], v[176:179], off
	v_add_f32_e32 v238, v238, v239
	v_add_f32_e32 v240, v240, v241
	v_add_f32_e32 v237, v238, v240
	global_load_dwordx4 v[94:97], v[242:243], off offset:512
	global_load_dwordx4 v[90:93], v[242:243], off offset:528
	s_waitcnt vmcnt(20)
	v_pk_add_f32 v[86:87], v[86:87], v[126:127]
	v_pk_add_f32 v[88:89], v[88:89], v[128:129]
	v_pk_add_f32 v[82:83], v[82:83], v[122:123]
	v_pk_add_f32 v[84:85], v[84:85], v[124:125]
	global_store_dwordx4 v[244:245], v[86:89], off offset:512
	global_store_dwordx4 v[244:245], v[82:85], off offset:528
	v_cvt_pk_bf16_f32 v220, v86, v87
	v_cvt_pk_bf16_f32 v221, v88, v89
	v_cvt_pk_bf16_f32 v222, v82, v83
	v_cvt_pk_bf16_f32 v223, v84, v85
	v_mul_f32_e32 v238, v87, v87
	v_mul_f32_e32 v240, v83, v83
	v_fmac_f32_e32 v238, v86, v86
	v_mul_f32_e32 v239, v89, v89
	v_fmac_f32_e32 v240, v82, v82
	v_mul_f32_e32 v241, v85, v85
	v_fmac_f32_e32 v239, v88, v88
	v_fmac_f32_e32 v241, v84, v84
	global_store_dwordx4 v[246:247], v[220:223], off offset:256
	v_add_f32_e32 v238, v238, v239
	v_add_f32_e32 v240, v240, v241
	v_add_f32_e32 v238, v238, v240
	v_add_f32_e32 v237, v237, v238
	ds_bpermute_b32 v250, v235, v237
	s_mov_b32 s24, 0x90000
	v_lshl_add_u64 v[242:243], s[24:25], 0, v[174:175]
	global_load_dwordx4 v[86:89], v[242:243], off
	global_load_dwordx4 v[82:85], v[242:243], off offset:16
	s_waitcnt lgkmcnt(0)
	v_add_f32_e32 v237, v237, v250
	ds_bpermute_b32 v250, v236, v237
	s_waitcnt lgkmcnt(0)
	s_and_saveexec_b64 s[0:1], s[26:27]
	v_add_f32_e32 v237, v237, v250
	global_store_dword v[248:249], v237, off offset:2048
	s_or_b64 exec, exec, s[0:1]
	s_waitcnt vmcnt(20)
	v_pk_add_f32 v[78:79], v[78:79], v[118:119]
	v_pk_add_f32 v[80:81], v[80:81], v[120:121]
	v_pk_add_f32 v[74:75], v[74:75], v[114:115]
	v_pk_add_f32 v[76:77], v[76:77], v[116:117]
	s_mov_b32 s24, 0x30000
	v_lshl_add_u64 v[244:245], s[24:25], 0, v[174:175]
	s_mov_b32 s24, 0x18000
	v_lshl_add_u64 v[246:247], s[24:25], 0, v[166:167]
	global_store_dwordx4 v[244:245], v[78:81], off
	global_store_dwordx4 v[244:245], v[74:77], off offset:16
	v_cvt_pk_bf16_f32 v176, v78, v79
	v_cvt_pk_bf16_f32 v177, v80, v81
	v_cvt_pk_bf16_f32 v178, v74, v75
	v_cvt_pk_bf16_f32 v179, v76, v77
	v_mul_f32_e32 v238, v79, v79
	v_mul_f32_e32 v240, v75, v75
	v_fmac_f32_e32 v238, v78, v78
	v_mul_f32_e32 v239, v81, v81
	v_fmac_f32_e32 v240, v74, v74
	v_mul_f32_e32 v241, v77, v77
	v_fmac_f32_e32 v239, v80, v80
	v_fmac_f32_e32 v241, v76, v76
	global_store_dwordx4 v[246:247], v[176:179], off
	v_add_f32_e32 v238, v238, v239
	v_add_f32_e32 v240, v240, v241
	v_add_f32_e32 v237, v238, v240
	global_load_dwordx4 v[78:81], v[242:243], off offset:512
	global_load_dwordx4 v[74:77], v[242:243], off offset:528
	s_waitcnt vmcnt(20)
	v_pk_add_f32 v[70:71], v[70:71], v[110:111]
	v_pk_add_f32 v[72:73], v[72:73], v[112:113]
	v_pk_add_f32 v[66:67], v[66:67], v[106:107]
	v_pk_add_f32 v[68:69], v[68:69], v[108:109]
	global_store_dwordx4 v[244:245], v[70:73], off offset:512
	global_store_dwordx4 v[244:245], v[66:69], off offset:528
	v_cvt_pk_bf16_f32 v220, v70, v71
	v_cvt_pk_bf16_f32 v221, v72, v73
	v_cvt_pk_bf16_f32 v222, v66, v67
	v_cvt_pk_bf16_f32 v223, v68, v69
	v_mul_f32_e32 v238, v71, v71
	v_mul_f32_e32 v240, v67, v67
	v_fmac_f32_e32 v238, v70, v70
	v_mul_f32_e32 v239, v73, v73
	v_fmac_f32_e32 v240, v66, v66
	v_mul_f32_e32 v241, v69, v69
	v_fmac_f32_e32 v239, v72, v72
	v_fmac_f32_e32 v241, v68, v68
	global_store_dwordx4 v[246:247], v[220:223], off offset:256
	v_add_f32_e32 v238, v238, v239
	v_add_f32_e32 v240, v240, v241
	v_add_f32_e32 v238, v238, v240
	v_add_f32_e32 v237, v237, v238
	ds_bpermute_b32 v250, v235, v237
	s_mov_b32 s24, 0xa0000
	v_lshl_add_u64 v[242:243], s[24:25], 0, v[174:175]
	global_load_dwordx4 v[70:73], v[242:243], off
	global_load_dwordx4 v[66:69], v[242:243], off offset:16
	s_waitcnt lgkmcnt(0)
; __device__ __forceinline__ unsigned pk2hw(float lo, float hi) { unsigned r; asm("s_nop 1\n\tv_cvt_pk_bf16_f32 %0, %1, %2" : "=v"(r) : "v"(lo), "v"(hi)); return r; }
;     __device__ __forceinline__ void operator()(const f32x4 (&acc)[2][2][4][2], const Unit& u, int wr, int wc, int fr, int fq) const {
;         asm volatile("" : "+v"(fr), "+v"(fq));
;         const int row0 = u.pm * 256 + wr * 64 + fr, col0 = u.pn * 256 + wc * 32 + 8 * fq;
; #pragma unroll
;         for (int ai = 0; ai < 2; ++ai)
; #pragma unroll
;             for (int m = 0; m < 4; ++m) { const int row = row0 + ai * 128 + m * 16; float sq = 0.f;
; #pragma unroll
;                 for (int bj = 0; bj < 2; ++bj) { const size_t off = (size_t)row * D + col0 + bj * 128;
;                     const f32x4 x0 = *(const f32x4*)(xin + off) + acc[ai][bj][m][0], x1 = *(const f32x4*)(xin + off + 4) + acc[ai][bj][m][1];
;                     *(f32x4*)(xout + off) = x0; *(f32x4*)(xout + off + 4) = x1;
;                     u32x4 w; w.x = pk2hw(x0[0], x0[1]); w.y = pk2hw(x0[2], x0[3]); w.z = pk2hw(x1[0], x1[1]); w.w = pk2hw(x1[2], x1[3]); *(u32x4*)(xb + off) = w;
;                     sq += ((x0[0] * x0[0] + x0[1] * x0[1]) + (x0[2] * x0[2] + x0[3] * x0[3])) + ((x1[0] * x1[0] + x1[1] * x1[1]) + (x1[2] * x1[2] + x1[3] * x1[3])); }
;                 sq += __shfl_xor(sq, 16); sq += __shfl_xor(sq, 32);
;                 if (fq == 0) ssn[(size_t)row * 16 + u.pn * 4 + wc] = sq; }
;     }
	v_add_f32_e32 v237, v237, v250
	ds_bpermute_b32 v250, v236, v237
	s_waitcnt lgkmcnt(0)
	s_and_saveexec_b64 s[0:1], s[26:27]
	v_add_f32_e32 v237, v237, v250
	global_store_dword v[248:249], v237, off offset:3072
	s_or_b64 exec, exec, s[0:1]
	s_waitcnt vmcnt(20)
	v_pk_add_f32 v[62:63], v[62:63], v[102:103]
	v_pk_add_f32 v[64:65], v[64:65], v[104:105]
	v_pk_add_f32 v[58:59], v[58:59], v[98:99]
	v_pk_add_f32 v[60:61], v[60:61], v[100:101]
	s_mov_b32 s24, 0x80000
	v_lshl_add_u64 v[244:245], s[24:25], 0, v[174:175]
	s_mov_b32 s24, 0x40000
	v_lshl_add_u64 v[246:247], s[24:25], 0, v[166:167]
	global_store_dwordx4 v[244:245], v[62:65], off
	global_store_dwordx4 v[244:245], v[58:61], off offset:16
	v_cvt_pk_bf16_f32 v176, v62, v63
	v_cvt_pk_bf16_f32 v177, v64, v65
	v_cvt_pk_bf16_f32 v178, v58, v59
	v_cvt_pk_bf16_f32 v179, v60, v61
	v_mul_f32_e32 v238, v63, v63
	v_mul_f32_e32 v240, v59, v59
	v_fmac_f32_e32 v238, v62, v62
	v_mul_f32_e32 v239, v65, v65
	v_fmac_f32_e32 v240, v58, v58
	v_mul_f32_e32 v241, v61, v61
	v_fmac_f32_e32 v239, v64, v64
	v_fmac_f32_e32 v241, v60, v60
	global_store_dwordx4 v[246:247], v[176:179], off
	v_add_f32_e32 v238, v238, v239
	v_add_f32_e32 v240, v240, v241
	v_add_f32_e32 v237, v238, v240
	global_load_dwordx4 v[62:65], v[242:243], off offset:512
	global_load_dwordx4 v[58:61], v[242:243], off offset:528
	s_waitcnt vmcnt(20)
	v_pk_add_f32 v[54:55], v[54:55], v[94:95]
	v_pk_add_f32 v[56:57], v[56:57], v[96:97]
	v_pk_add_f32 v[50:51], v[50:51], v[90:91]
	v_pk_add_f32 v[52:53], v[52:53], v[92:93]
	global_store_dwordx4 v[244:245], v[54:57], off offset:512
	global_store_dwordx4 v[244:245], v[50:53], off offset:528
	v_cvt_pk_bf16_f32 v220, v54, v55
	v_cvt_pk_bf16_f32 v221, v56, v57
	v_cvt_pk_bf16_f32 v222, v50, v51
	v_cvt_pk_bf16_f32 v223, v52, v53
	v_mul_f32_e32 v238, v55, v55
	v_mul_f32_e32 v240, v51, v51
	v_fmac_f32_e32 v238, v54, v54
	v_mul_f32_e32 v239, v57, v57
	v_fmac_f32_e32 v240, v50, v50
	v_mul_f32_e32 v241, v53, v53
	v_fmac_f32_e32 v239, v56, v56
	v_fmac_f32_e32 v241, v52, v52
	global_store_dwordx4 v[246:247], v[220:223], off offset:256
	v_add_f32_e32 v238, v238, v239
	v_add_f32_e32 v240, v240, v241
	v_add_f32_e32 v238, v238, v240
	v_add_f32_e32 v237, v237, v238
	ds_bpermute_b32 v250, v235, v237
	s_mov_b32 s24, 0xb0000
	v_lshl_add_u64 v[242:243], s[24:25], 0, v[174:175]
	global_load_dwordx4 v[54:57], v[242:243], off
	global_load_dwordx4 v[50:53], v[242:243], off offset:16
	s_waitcnt lgkmcnt(0)
	v_add_f32_e32 v237, v237, v250
	ds_bpermute_b32 v250, v236, v237
	s_waitcnt lgkmcnt(0)
	s_and_saveexec_b64 s[0:1], s[26:27]
	v_add_f32_e32 v237, v237, v250
	global_store_dword v[142:143], v237, off
	s_or_b64 exec, exec, s[0:1]
	s_waitcnt vmcnt(20)
	v_pk_add_f32 v[46:47], v[46:47], v[86:87]
	v_pk_add_f32 v[48:49], v[48:49], v[88:89]
	v_pk_add_f32 v[42:43], v[42:43], v[82:83]
	v_pk_add_f32 v[44:45], v[44:45], v[84:85]
	s_mov_b32 s24, 0x90000
	v_lshl_add_u64 v[244:245], s[24:25], 0, v[174:175]
	s_mov_b32 s24, 0x48000
	v_lshl_add_u64 v[246:247], s[24:25], 0, v[166:167]
	global_store_dwordx4 v[244:245], v[46:49], off
	global_store_dwordx4 v[244:245], v[42:45], off offset:16
	v_cvt_pk_bf16_f32 v176, v46, v47
	v_cvt_pk_bf16_f32 v177, v48, v49
	v_cvt_pk_bf16_f32 v178, v42, v43
	v_cvt_pk_bf16_f32 v179, v44, v45
	v_mul_f32_e32 v238, v47, v47
	v_mul_f32_e32 v240, v43, v43
	v_fmac_f32_e32 v238, v46, v46
	v_mul_f32_e32 v239, v49, v49
	v_fmac_f32_e32 v240, v42, v42
	v_mul_f32_e32 v241, v45, v45
	v_fmac_f32_e32 v239, v48, v48
	v_fmac_f32_e32 v241, v44, v44
	global_store_dwordx4 v[246:247], v[176:179], off
	v_add_f32_e32 v238, v238, v239
	v_add_f32_e32 v240, v240, v241
	v_add_f32_e32 v237, v238, v240
	global_load_dwordx4 v[46:49], v[242:243], off offset:512
	global_load_dwordx4 v[42:45], v[242:243], off offset:528
	s_waitcnt vmcnt(20)
	v_pk_add_f32 v[38:39], v[38:39], v[78:79]
	v_pk_add_f32 v[40:41], v[40:41], v[80:81]
	v_pk_add_f32 v[34:35], v[34:35], v[74:75]
	v_pk_add_f32 v[36:37], v[36:37], v[76:77]
	global_store_dwordx4 v[244:245], v[38:41], off offset:512
	global_store_dwordx4 v[244:245], v[34:37], off offset:528
	v_cvt_pk_bf16_f32 v220, v38, v39
	v_cvt_pk_bf16_f32 v221, v40, v41
	v_cvt_pk_bf16_f32 v222, v34, v35
	v_cvt_pk_bf16_f32 v223, v36, v37
	v_mul_f32_e32 v238, v39, v39
	v_mul_f32_e32 v240, v35, v35
	v_fmac_f32_e32 v238, v38, v38
	v_mul_f32_e32 v239, v41, v41
	v_fmac_f32_e32 v240, v34, v34
	v_mul_f32_e32 v241, v37, v37
	v_fmac_f32_e32 v239, v40, v40
	v_fmac_f32_e32 v241, v36, v36
	global_store_dwordx4 v[246:247], v[220:223], off offset:256
	v_add_f32_e32 v238, v238, v239
	v_add_f32_e32 v240, v240, v241
	v_add_f32_e32 v238, v238, v240
	v_add_f32_e32 v237, v237, v238
	ds_bpermute_b32 v250, v235, v237
	s_waitcnt lgkmcnt(0)
; __device__ __forceinline__ unsigned pk2hw(float lo, float hi) { unsigned r; asm("s_nop 1\n\tv_cvt_pk_bf16_f32 %0, %1, %2" : "=v"(r) : "v"(lo), "v"(hi)); return r; }
;     __device__ __forceinline__ void operator()(const f32x4 (&acc)[2][2][4][2], const Unit& u, int wr, int wc, int fr, int fq) const {
;         asm volatile("" : "+v"(fr), "+v"(fq));
;         const int row0 = u.pm * 256 + wr * 64 + fr, col0 = u.pn * 256 + wc * 32 + 8 * fq;
; #pragma unroll
;         for (int ai = 0; ai < 2; ++ai)
; #pragma unroll
;             for (int m = 0; m < 4; ++m) { const int row = row0 + ai * 128 + m * 16; float sq = 0.f;
; #pragma unroll
;                 for (int bj = 0; bj < 2; ++bj) { const size_t off = (size_t)row * D + col0 + bj * 128;
;                     const f32x4 x0 = *(const f32x4*)(xin + off) + acc[ai][bj][m][0], x1 = *(const f32x4*)(xin + off + 4) + acc[ai][bj][m][1];
;                     *(f32x4*)(xout + off) = x0; *(f32x4*)(xout + off + 4) = x1;
;                     u32x4 w; w.x = pk2hw(x0[0], x0[1]); w.y = pk2hw(x0[2], x0[3]); w.z = pk2hw(x1[0], x1[1]); w.w = pk2hw(x1[2], x1[3]); *(u32x4*)(xb + off) = w;
;                     sq += ((x0[0] * x0[0] + x0[1] * x0[1]) + (x0[2] * x0[2] + x0[3] * x0[3])) + ((x1[0] * x1[0] + x1[1] * x1[1]) + (x1[2] * x1[2] + x1[3] * x1[3])); }
;                 sq += __shfl_xor(sq, 16); sq += __shfl_xor(sq, 32);
;                 if (fq == 0) ssn[(size_t)row * 16 + u.pn * 4 + wc] = sq; }
;     }
	v_add_f32_e32 v237, v237, v250
	ds_bpermute_b32 v250, v236, v237
	s_waitcnt lgkmcnt(0)
	s_and_saveexec_b64 s[0:1], s[26:27]
	v_add_f32_e32 v237, v237, v250
	global_store_dword v[142:143], v237, off offset:1024
	s_or_b64 exec, exec, s[0:1]
	s_waitcnt vmcnt(18)
	v_pk_add_f32 v[30:31], v[30:31], v[70:71]
	v_pk_add_f32 v[32:33], v[32:33], v[72:73]
	v_pk_add_f32 v[26:27], v[26:27], v[66:67]
	v_pk_add_f32 v[28:29], v[28:29], v[68:69]
	s_mov_b32 s24, 0xa0000
	v_lshl_add_u64 v[244:245], s[24:25], 0, v[174:175]
	s_mov_b32 s24, 0x50000
	v_lshl_add_u64 v[246:247], s[24:25], 0, v[166:167]
	global_store_dwordx4 v[244:245], v[30:33], off
	global_store_dwordx4 v[244:245], v[26:29], off offset:16
	v_cvt_pk_bf16_f32 v176, v30, v31
	v_cvt_pk_bf16_f32 v177, v32, v33
	v_cvt_pk_bf16_f32 v178, v26, v27
	v_cvt_pk_bf16_f32 v179, v28, v29
	v_mul_f32_e32 v238, v31, v31
	v_mul_f32_e32 v240, v27, v27
	v_fmac_f32_e32 v238, v30, v30
	v_mul_f32_e32 v239, v33, v33
	v_fmac_f32_e32 v240, v26, v26
	v_mul_f32_e32 v241, v29, v29
	v_fmac_f32_e32 v239, v32, v32
	v_fmac_f32_e32 v241, v28, v28
	global_store_dwordx4 v[246:247], v[176:179], off
	v_add_f32_e32 v238, v238, v239
	v_add_f32_e32 v240, v240, v241
	v_add_f32_e32 v237, v238, v240
	s_waitcnt vmcnt(16)
	v_pk_add_f32 v[22:23], v[22:23], v[62:63]
	v_pk_add_f32 v[24:25], v[24:25], v[64:65]
	v_pk_add_f32 v[18:19], v[18:19], v[58:59]
	v_pk_add_f32 v[20:21], v[20:21], v[60:61]
	global_store_dwordx4 v[244:245], v[22:25], off offset:512
	global_store_dwordx4 v[244:245], v[18:21], off offset:528
	v_cvt_pk_bf16_f32 v220, v22, v23
	v_cvt_pk_bf16_f32 v221, v24, v25
	v_cvt_pk_bf16_f32 v222, v18, v19
	v_cvt_pk_bf16_f32 v223, v20, v21
	v_mul_f32_e32 v238, v23, v23
	v_mul_f32_e32 v240, v19, v19
	v_fmac_f32_e32 v238, v22, v22
	v_mul_f32_e32 v239, v25, v25
	v_fmac_f32_e32 v240, v18, v18
	v_mul_f32_e32 v241, v21, v21
	v_fmac_f32_e32 v239, v24, v24
	v_fmac_f32_e32 v241, v20, v20
	global_store_dwordx4 v[246:247], v[220:223], off offset:256
	v_add_f32_e32 v238, v238, v239
	v_add_f32_e32 v240, v240, v241
	v_add_f32_e32 v238, v238, v240
	v_add_f32_e32 v237, v237, v238
	ds_bpermute_b32 v250, v235, v237
	s_waitcnt lgkmcnt(0)
	v_add_f32_e32 v237, v237, v250
	ds_bpermute_b32 v250, v236, v237
	s_waitcnt lgkmcnt(0)
	s_and_saveexec_b64 s[0:1], s[26:27]
	v_add_f32_e32 v237, v237, v250
	global_store_dword v[142:143], v237, off offset:2048
	s_or_b64 exec, exec, s[0:1]
	s_waitcnt vmcnt(14)
	v_pk_add_f32 v[14:15], v[14:15], v[54:55]
	v_pk_add_f32 v[16:17], v[16:17], v[56:57]
	v_pk_add_f32 v[10:11], v[10:11], v[50:51]
	v_pk_add_f32 v[12:13], v[12:13], v[52:53]
	s_mov_b32 s24, 0xb0000
	v_lshl_add_u64 v[244:245], s[24:25], 0, v[174:175]
	s_mov_b32 s24, 0x58000
	v_lshl_add_u64 v[246:247], s[24:25], 0, v[166:167]
	global_store_dwordx4 v[244:245], v[14:17], off
	global_store_dwordx4 v[244:245], v[10:13], off offset:16
	v_cvt_pk_bf16_f32 v176, v14, v15
	v_cvt_pk_bf16_f32 v177, v16, v17
	v_cvt_pk_bf16_f32 v178, v10, v11
	v_cvt_pk_bf16_f32 v179, v12, v13
	v_mul_f32_e32 v238, v15, v15
	v_mul_f32_e32 v240, v11, v11
	v_fmac_f32_e32 v238, v14, v14
	v_mul_f32_e32 v239, v17, v17
	v_fmac_f32_e32 v240, v10, v10
	v_mul_f32_e32 v241, v13, v13
	v_fmac_f32_e32 v239, v16, v16
	v_fmac_f32_e32 v241, v12, v12
	global_store_dwordx4 v[246:247], v[176:179], off
	v_add_f32_e32 v238, v238, v239
	v_add_f32_e32 v240, v240, v241
	v_add_f32_e32 v237, v238, v240
	s_waitcnt vmcnt(12)
	v_pk_add_f32 v[6:7], v[6:7], v[46:47]
	v_pk_add_f32 v[8:9], v[8:9], v[48:49]
	v_pk_add_f32 v[2:3], v[2:3], v[42:43]
	v_pk_add_f32 v[4:5], v[4:5], v[44:45]
	global_store_dwordx4 v[244:245], v[6:9], off offset:512
	global_store_dwordx4 v[244:245], v[2:5], off offset:528
	v_cvt_pk_bf16_f32 v220, v6, v7
	v_cvt_pk_bf16_f32 v221, v8, v9
	v_cvt_pk_bf16_f32 v222, v2, v3
	v_cvt_pk_bf16_f32 v223, v4, v5
	v_mul_f32_e32 v238, v7, v7
	v_mul_f32_e32 v240, v3, v3
	v_fmac_f32_e32 v238, v6, v6
	v_mul_f32_e32 v239, v9, v9
	v_fmac_f32_e32 v240, v2, v2
	v_mul_f32_e32 v241, v5, v5
	v_fmac_f32_e32 v239, v8, v8
	v_fmac_f32_e32 v241, v4, v4
	global_store_dwordx4 v[246:247], v[220:223], off offset:256
	v_add_f32_e32 v238, v238, v239
	v_add_f32_e32 v240, v240, v241
	v_add_f32_e32 v238, v238, v240
	v_add_f32_e32 v237, v237, v238
	ds_bpermute_b32 v250, v235, v237
	s_waitcnt lgkmcnt(0)
	v_add_f32_e32 v237, v237, v250
	ds_bpermute_b32 v250, v236, v237
	s_waitcnt lgkmcnt(0)
	s_and_saveexec_b64 s[0:1], s[26:27]
	v_add_f32_e32 v237, v237, v250
	global_store_dword v[142:143], v237, off offset:3072
	s_or_b64 exec, exec, s[0:1]
	s_and_b64 vcc, exec, s[4:5]
	s_mov_b64 s[0:1], -1
	s_cbranch_vccnz .LBB0_1091
	s_andn2_b64 vcc, exec, s[10:11]
	s_cbranch_vccnz .LBB0_1090
	s_barrier
	s_branch .LBB0_1090
